# pair order boustrophedon (every transition between consecutive same-accumulator pairs keeps the srcA or the srcB fragment pair), all four GEMM loops
# speedup vs baseline: 1.0109x; 1.0109x over previous
; #define PG8_STAGE(bufoff, gbase, voff) do { _Pragma("unroll") for (int _i = 0; _i < 2; ++_i) \
;         __builtin_amdgcn_global_load_lds((const unsigned*)((const char*)(gbase) + (voff)[_i]), (PG8_LAS unsigned*)(lds + (bufoff) + ldsw + _i * 8192), 16, 0, 0); } while (0)
; #define PG8_LDA(dst, b, h) do { _Pragma("unroll") for (int m = 0; m < 4; ++m) _Pragma("unroll") for (int k = 0; k < 2; ++k) dst[m][k] = *(const PG8_LAS bf16x8*)(lds + PG8_SA(b, h) + aoff + m * 2048 + k * 1024); } while (0)
; #define PG8_LDB(dst, b, h) do { _Pragma("unroll") for (int n = 0; n < 2; ++n) _Pragma("unroll") for (int k = 0; k < 2; ++k) dst[n][k] = *(const PG8_LAS bf16x8*)(lds + PG8_SB(b, h) + boff + n * 2048 + k * 1024); } while (0)
; #define PG8_MMA(ai, bj, At, Bt) do { __builtin_amdgcn_s_setprio(1); _Pragma("unroll") for (int m = 0; m < 4; ++m) _Pragma("unroll") for (int n = 0; n < 2; ++n) _Pragma("unroll") for (int k = 0; k < 2; ++k) \
;         acc[ai][bj][m][n] = __builtin_amdgcn_mfma_f32_16x16x32_bf16(Bt[n][k], At[m][k], acc[ai][bj][m][n], 0, 0, 0); __builtin_amdgcn_s_setprio(0); } while (0)
; #define PG8_WAIT_V(n) asm volatile("s_waitcnt vmcnt(" #n ")" ::: "memory")
; #define PG8_WAIT_L(n) asm volatile("s_waitcnt lgkmcnt(" #n ")" ::: "memory")
; #define PG8_BAR __builtin_amdgcn_s_barrier()
; #define PG8_SCHED __builtin_amdgcn_sched_barrier(0)
; template <class Epi, class Sched, bool ALIGN_EPI = false, bool SP2 = false>
; __device__ __forceinline__ void gemm_phase(PG8_LAS unsigned char* lds, const Gemm g, const Sched& S, const Epi& E) {
;     ...
;             PG8_LDB(B0, 0, 0); PG8_LDB(B1, 0, 1); PG8_SCHED; PG8_LDA(At, 0, 0); PG8_STAGE(PG8_SA(1, 1), a1 + hstep, voffA);
;             PG8_WAIT_V(8); PG8_WAIT_L(0); PG8_BAR; PG8_MMA(0, 0, At, B0); PG8_MMA(0, 1, At, B1); PG8_BAR; PG8_SCHED;
;             PG8_LDA(At, 0, 1); PG8_STAGE(PG8_SB(0, 0), b2, voffB); PG8_STAGE(PG8_SB(0, 1), b2 + hstep, voffB); PG8_STAGE(PG8_SA(0, 0), a2, voffA);
;             PG8_WAIT_V(8); PG8_WAIT_L(0); PG8_BAR; PG8_MMA(1, 0, At, B0); PG8_MMA(1, 1, At, B1); PG8_BAR; PG8_SCHED;
.LBB0_349:
	ds_read_b128 v[150:153], v169
	ds_read_b128 v[154:157], v169 offset:1024
	ds_read_b128 v[158:161], v169 offset:2048
	ds_read_b128 v[162:165], v169 offset:3072
	ds_read_b128 v[174:177], v170
	ds_read_b128 v[178:181], v170 offset:1024
	ds_read_b128 v[182:185], v170 offset:2048
	ds_read_b128 v[186:189], v170 offset:3072
	s_add_u32 s0, s88, 0xfff00080
	s_addc_u32 s1, s89, -1
	s_cmp_eq_u32 s23, 60
	s_cselect_b32 s93, s51, s1
	s_cselect_b32 s92, s50, s0
	s_cselect_b32 s91, s53, s21
	s_cselect_b32 s90, s52, s9
	ds_read_b128 v[190:193], v171
	ds_read_b128 v[196:199], v171 offset:1024
	ds_read_b128 v[200:203], v171 offset:2048
	ds_read_b128 v[204:207], v171 offset:3072
	ds_read_b128 v[208:211], v171 offset:4096
	ds_read_b128 v[212:215], v171 offset:5120
	ds_read_b128 v[220:223], v171 offset:6144
	ds_read_b128 v[224:227], v171 offset:7168
	s_add_u32 s0, s88, 0xfff00000
	s_addc_u32 s1, s89, -1
	s_add_i32 m0, s27, 0x8000
	s_nop 0
	global_load_lds_dwordx4 v134, s[0:1]
	s_add_i32 m0, s27, 0xa000
	s_nop 0
	global_load_lds_dwordx4 v138, s[0:1]
	s_add_i32 m0, s27, 0xc000
	s_nop 0
	global_load_lds_dwordx4 v134, s[88:89]
	s_add_i32 m0, s27, 0xe000
	s_nop 0
	global_load_lds_dwordx4 v138, s[88:89]
	s_waitcnt lgkmcnt(0)
	s_setprio 1
	v_mfma_f32_16x16x32_bf16 v[38:41], v[150:153], v[190:193], v[38:41]
	v_mfma_f32_16x16x32_bf16 v[38:41], v[154:157], v[196:199], v[38:41]
	v_mfma_f32_16x16x32_bf16 v[30:33], v[158:161], v[190:193], v[30:33]
	v_mfma_f32_16x16x32_bf16 v[30:33], v[162:165], v[196:199], v[30:33]
	v_mfma_f32_16x16x32_bf16 v[50:53], v[174:177], v[190:193], v[50:53]
	v_mfma_f32_16x16x32_bf16 v[50:53], v[178:181], v[196:199], v[50:53]
	v_mfma_f32_16x16x32_bf16 v[46:49], v[182:185], v[190:193], v[46:49]
	v_mfma_f32_16x16x32_bf16 v[46:49], v[186:189], v[196:199], v[46:49]
	v_mfma_f32_16x16x32_bf16 v[118:121], v[182:185], v[200:203], v[118:121]
	v_mfma_f32_16x16x32_bf16 v[118:121], v[186:189], v[204:207], v[118:121]
	v_mfma_f32_16x16x32_bf16 v[122:125], v[174:177], v[200:203], v[122:125]
	v_mfma_f32_16x16x32_bf16 v[122:125], v[178:181], v[204:207], v[122:125]
	v_mfma_f32_16x16x32_bf16 v[126:129], v[158:161], v[200:203], v[126:129]
	v_mfma_f32_16x16x32_bf16 v[126:129], v[162:165], v[204:207], v[126:129]
	v_mfma_f32_16x16x32_bf16 v[130:133], v[150:153], v[200:203], v[130:133]
	v_mfma_f32_16x16x32_bf16 v[130:133], v[154:157], v[204:207], v[130:133]
	v_mfma_f32_16x16x32_bf16 v[114:117], v[150:153], v[208:211], v[114:117]
	v_mfma_f32_16x16x32_bf16 v[114:117], v[154:157], v[212:215], v[114:117]
	v_mfma_f32_16x16x32_bf16 v[110:113], v[158:161], v[208:211], v[110:113]
	v_mfma_f32_16x16x32_bf16 v[110:113], v[162:165], v[212:215], v[110:113]
	v_mfma_f32_16x16x32_bf16 v[106:109], v[174:177], v[208:211], v[106:109]
	v_mfma_f32_16x16x32_bf16 v[106:109], v[178:181], v[212:215], v[106:109]
	v_mfma_f32_16x16x32_bf16 v[102:105], v[182:185], v[208:211], v[102:105]
	v_mfma_f32_16x16x32_bf16 v[102:105], v[186:189], v[212:215], v[102:105]
	v_mfma_f32_16x16x32_bf16 v[86:89], v[182:185], v[220:223], v[86:89]
	v_mfma_f32_16x16x32_bf16 v[86:89], v[186:189], v[224:227], v[86:89]
	v_mfma_f32_16x16x32_bf16 v[90:93], v[174:177], v[220:223], v[90:93]
	v_mfma_f32_16x16x32_bf16 v[90:93], v[178:181], v[224:227], v[90:93]
	v_mfma_f32_16x16x32_bf16 v[94:97], v[158:161], v[220:223], v[94:97]
	v_mfma_f32_16x16x32_bf16 v[94:97], v[162:165], v[224:227], v[94:97]
	v_mfma_f32_16x16x32_bf16 v[98:101], v[150:153], v[220:223], v[98:101]
	v_mfma_f32_16x16x32_bf16 v[98:101], v[154:157], v[224:227], v[98:101]
	s_setprio 0
	s_waitcnt vmcnt(8)
	s_barrier
	ds_read_b128 v[190:193], v171 offset:16384
	ds_read_b128 v[196:199], v171 offset:17408
	ds_read_b128 v[200:203], v171 offset:18432
	ds_read_b128 v[204:207], v171 offset:19456
	ds_read_b128 v[208:211], v171 offset:20480
	ds_read_b128 v[212:215], v171 offset:21504
	ds_read_b128 v[220:223], v171 offset:22528
	ds_read_b128 v[224:227], v171 offset:23552
	s_add_u32 vcc_lo, s90, 0x100000
	s_addc_u32 vcc_hi, s91, 0
	s_add_i32 m0, s27, 0x10000
	s_nop 0
	global_load_lds_dwordx4 v136, s[90:91]
	s_add_i32 m0, s27, 0x12000
	s_nop 0
	global_load_lds_dwordx4 v140, s[90:91]
	s_add_i32 m0, s27, 0x14000
	s_nop 0
	global_load_lds_dwordx4 v136, vcc
	s_add_i32 m0, s27, 0x16000
	s_nop 0
	global_load_lds_dwordx4 v140, vcc
	s_waitcnt lgkmcnt(0)
	s_setprio 1
	v_mfma_f32_16x16x32_bf16 v[82:85], v[150:153], v[190:193], v[82:85]
	v_mfma_f32_16x16x32_bf16 v[82:85], v[154:157], v[196:199], v[82:85]
	v_mfma_f32_16x16x32_bf16 v[78:81], v[158:161], v[190:193], v[78:81]
	v_mfma_f32_16x16x32_bf16 v[78:81], v[162:165], v[196:199], v[78:81]
	v_mfma_f32_16x16x32_bf16 v[74:77], v[174:177], v[190:193], v[74:77]
	v_mfma_f32_16x16x32_bf16 v[74:77], v[178:181], v[196:199], v[74:77]
	v_mfma_f32_16x16x32_bf16 v[70:73], v[182:185], v[190:193], v[70:73]
	v_mfma_f32_16x16x32_bf16 v[70:73], v[186:189], v[196:199], v[70:73]
	v_mfma_f32_16x16x32_bf16 v[54:57], v[182:185], v[200:203], v[54:57]
	v_mfma_f32_16x16x32_bf16 v[54:57], v[186:189], v[204:207], v[54:57]
	v_mfma_f32_16x16x32_bf16 v[58:61], v[174:177], v[200:203], v[58:61]
	v_mfma_f32_16x16x32_bf16 v[58:61], v[178:181], v[204:207], v[58:61]
	v_mfma_f32_16x16x32_bf16 v[62:65], v[158:161], v[200:203], v[62:65]
	v_mfma_f32_16x16x32_bf16 v[62:65], v[162:165], v[204:207], v[62:65]
	v_mfma_f32_16x16x32_bf16 v[66:69], v[150:153], v[200:203], v[66:69]
	v_mfma_f32_16x16x32_bf16 v[66:69], v[154:157], v[204:207], v[66:69]
	v_mfma_f32_16x16x32_bf16 v[42:45], v[150:153], v[208:211], v[42:45]
	v_mfma_f32_16x16x32_bf16 v[42:45], v[154:157], v[212:215], v[42:45]
	v_mfma_f32_16x16x32_bf16 v[34:37], v[158:161], v[208:211], v[34:37]
	v_mfma_f32_16x16x32_bf16 v[34:37], v[162:165], v[212:215], v[34:37]
	v_mfma_f32_16x16x32_bf16 v[26:29], v[174:177], v[208:211], v[26:29]
	v_mfma_f32_16x16x32_bf16 v[26:29], v[178:181], v[212:215], v[26:29]
	v_mfma_f32_16x16x32_bf16 v[22:25], v[182:185], v[208:211], v[22:25]
	v_mfma_f32_16x16x32_bf16 v[22:25], v[186:189], v[212:215], v[22:25]
	v_mfma_f32_16x16x32_bf16 v[4:7], v[182:185], v[220:223], v[6:9]
	v_mfma_f32_16x16x32_bf16 v[4:7], v[186:189], v[224:227], v[4:7]
	v_mfma_f32_16x16x32_bf16 v[10:13], v[174:177], v[220:223], v[10:13]
	v_mfma_f32_16x16x32_bf16 v[10:13], v[178:181], v[224:227], v[10:13]
	v_mfma_f32_16x16x32_bf16 v[14:17], v[158:161], v[220:223], v[14:17]
	v_mfma_f32_16x16x32_bf16 v[14:17], v[162:165], v[224:227], v[14:17]
	v_mfma_f32_16x16x32_bf16 v[18:21], v[150:153], v[220:223], v[18:21]
	v_mfma_f32_16x16x32_bf16 v[18:21], v[154:157], v[224:227], v[18:21]
	s_setprio 0
	s_waitcnt vmcnt(6)
	s_barrier
; #define PG8_STAGE(bufoff, gbase, voff) do { _Pragma("unroll") for (int _i = 0; _i < 2; ++_i) \
;         __builtin_amdgcn_global_load_lds((const unsigned*)((const char*)(gbase) + (voff)[_i]), (PG8_LAS unsigned*)(lds + (bufoff) + ldsw + _i * 8192), 16, 0, 0); } while (0)
; #define PG8_LDA(dst, b, h) do { _Pragma("unroll") for (int m = 0; m < 4; ++m) _Pragma("unroll") for (int k = 0; k < 2; ++k) dst[m][k] = *(const PG8_LAS bf16x8*)(lds + PG8_SA(b, h) + aoff + m * 2048 + k * 1024); } while (0)
; #define PG8_LDB(dst, b, h) do { _Pragma("unroll") for (int n = 0; n < 2; ++n) _Pragma("unroll") for (int k = 0; k < 2; ++k) dst[n][k] = *(const PG8_LAS bf16x8*)(lds + PG8_SB(b, h) + boff + n * 2048 + k * 1024); } while (0)
; #define PG8_MMA(ai, bj, At, Bt) do { __builtin_amdgcn_s_setprio(1); _Pragma("unroll") for (int m = 0; m < 4; ++m) _Pragma("unroll") for (int n = 0; n < 2; ++n) _Pragma("unroll") for (int k = 0; k < 2; ++k) \
;         acc[ai][bj][m][n] = __builtin_amdgcn_mfma_f32_16x16x32_bf16(Bt[n][k], At[m][k], acc[ai][bj][m][n], 0, 0, 0); __builtin_amdgcn_s_setprio(0); } while (0)
; #define PG8_WAIT_V(n) asm volatile("s_waitcnt vmcnt(" #n ")" ::: "memory")
; #define PG8_WAIT_L(n) asm volatile("s_waitcnt lgkmcnt(" #n ")" ::: "memory")
; #define PG8_BAR __builtin_amdgcn_s_barrier()
; template <class Epi, class Sched, bool ALIGN_EPI = false, bool SP2 = false>
; __device__ __forceinline__ void gemm_phase(PG8_LAS unsigned char* lds, const Gemm g, const Sched& S, const Epi& E) {
;     ...
;         for (int t = 0; t < nt; t += 2) {
;             const bool last = (t == nt - 2);
;             const char* a1 = cA + (size_t)(t + 1) * kstep;
;             const char* a2 = last ? nA : cA + (size_t)(t + 2) * kstep; const char* b2 = last ? nB : cB + (size_t)(t + 2) * kstep;
;             const char* a3 = a2 + kstep; const char* b3 = b2 + kstep;
;     ...
;             PG8_LDB(B0, 1, 0); PG8_LDB(B1, 1, 1); PG8_SCHED; PG8_LDA(At, 1, 0); PG8_STAGE(PG8_SA(0, 1), a2 + hstep, voffA);
;             PG8_WAIT_V(8); PG8_WAIT_L(0); PG8_BAR; PG8_MMA(0, 0, At, B0); PG8_MMA(0, 1, At, B1); PG8_BAR; PG8_SCHED;
;             PG8_LDA(At, 1, 1); PG8_STAGE(PG8_SB(1, 0), b3, voffB); PG8_STAGE(PG8_SB(1, 1), b3 + hstep, voffB); PG8_STAGE(PG8_SA(1, 0), a3, voffA);
;             PG8_WAIT_V(8); PG8_WAIT_L(0); PG8_BAR; PG8_MMA(1, 0, At, B0); PG8_MMA(1, 1, At, B1); PG8_BAR; PG8_SCHED;
	s_add_i32 s0, 0, 0x18000
	v_add_u32_e32 v3, s0, v167
	s_add_i32 s1, 0, 0x1c000
	ds_read_b128 v[150:153], v3
	ds_read_b128 v[154:157], v3 offset:1024
	ds_read_b128 v[158:161], v3 offset:2048
	ds_read_b128 v[162:165], v3 offset:3072
	v_add_u32_e32 v3, s1, v167
	ds_read_b128 v[174:177], v3
	ds_read_b128 v[178:181], v3 offset:1024
	ds_read_b128 v[182:185], v3 offset:2048
	ds_read_b128 v[186:189], v3 offset:3072
	ds_read_b128 v[190:193], v171 offset:32768
	ds_read_b128 v[196:199], v171 offset:33792
	ds_read_b128 v[200:203], v171 offset:34816
	ds_read_b128 v[204:207], v171 offset:35840
	ds_read_b128 v[208:211], v171 offset:36864
	ds_read_b128 v[212:215], v171 offset:37888
	ds_read_b128 v[220:223], v171 offset:38912
	ds_read_b128 v[224:227], v171 offset:39936
	s_add_u32 vcc_lo, s92, 0x100000
	s_addc_u32 vcc_hi, s93, 0
	s_mov_b32 m0, s27
	s_nop 0
	global_load_lds_dwordx4 v134, s[92:93]
	s_add_i32 m0, s27, 0x2000
	s_nop 0
	global_load_lds_dwordx4 v138, s[92:93]
	s_add_i32 m0, s27, 0x4000
	s_nop 0
	global_load_lds_dwordx4 v134, vcc
	s_add_i32 m0, s27, 0x6000
	s_nop 0
	global_load_lds_dwordx4 v138, vcc
	s_waitcnt lgkmcnt(0)
	s_setprio 1
	v_mfma_f32_16x16x32_bf16 v[38:41], v[150:153], v[190:193], v[38:41]
	v_mfma_f32_16x16x32_bf16 v[38:41], v[154:157], v[196:199], v[38:41]
	v_mfma_f32_16x16x32_bf16 v[30:33], v[158:161], v[190:193], v[30:33]
	v_mfma_f32_16x16x32_bf16 v[30:33], v[162:165], v[196:199], v[30:33]
	v_mfma_f32_16x16x32_bf16 v[50:53], v[174:177], v[190:193], v[50:53]
	v_mfma_f32_16x16x32_bf16 v[50:53], v[178:181], v[196:199], v[50:53]
	v_mfma_f32_16x16x32_bf16 v[46:49], v[182:185], v[190:193], v[46:49]
	v_mfma_f32_16x16x32_bf16 v[46:49], v[186:189], v[196:199], v[46:49]
	v_mfma_f32_16x16x32_bf16 v[118:121], v[182:185], v[200:203], v[118:121]
	v_mfma_f32_16x16x32_bf16 v[118:121], v[186:189], v[204:207], v[118:121]
	v_mfma_f32_16x16x32_bf16 v[122:125], v[174:177], v[200:203], v[122:125]
	v_mfma_f32_16x16x32_bf16 v[122:125], v[178:181], v[204:207], v[122:125]
	v_mfma_f32_16x16x32_bf16 v[126:129], v[158:161], v[200:203], v[126:129]
	v_mfma_f32_16x16x32_bf16 v[126:129], v[162:165], v[204:207], v[126:129]
	v_mfma_f32_16x16x32_bf16 v[130:133], v[150:153], v[200:203], v[130:133]
	v_mfma_f32_16x16x32_bf16 v[130:133], v[154:157], v[204:207], v[130:133]
	v_mfma_f32_16x16x32_bf16 v[114:117], v[150:153], v[208:211], v[114:117]
	v_mfma_f32_16x16x32_bf16 v[114:117], v[154:157], v[212:215], v[114:117]
	v_mfma_f32_16x16x32_bf16 v[110:113], v[158:161], v[208:211], v[110:113]
	v_mfma_f32_16x16x32_bf16 v[110:113], v[162:165], v[212:215], v[110:113]
	v_mfma_f32_16x16x32_bf16 v[106:109], v[174:177], v[208:211], v[106:109]
	v_mfma_f32_16x16x32_bf16 v[106:109], v[178:181], v[212:215], v[106:109]
	v_mfma_f32_16x16x32_bf16 v[102:105], v[182:185], v[208:211], v[102:105]
	v_mfma_f32_16x16x32_bf16 v[102:105], v[186:189], v[212:215], v[102:105]
	v_mfma_f32_16x16x32_bf16 v[86:89], v[182:185], v[220:223], v[86:89]
	v_mfma_f32_16x16x32_bf16 v[86:89], v[186:189], v[224:227], v[86:89]
	v_mfma_f32_16x16x32_bf16 v[90:93], v[174:177], v[220:223], v[90:93]
	v_mfma_f32_16x16x32_bf16 v[90:93], v[178:181], v[224:227], v[90:93]
	v_mfma_f32_16x16x32_bf16 v[94:97], v[158:161], v[220:223], v[94:97]
	v_mfma_f32_16x16x32_bf16 v[94:97], v[162:165], v[224:227], v[94:97]
	v_mfma_f32_16x16x32_bf16 v[98:101], v[150:153], v[220:223], v[98:101]
	v_mfma_f32_16x16x32_bf16 v[98:101], v[154:157], v[224:227], v[98:101]
	s_setprio 0
	s_waitcnt vmcnt(8)
	s_barrier
	ds_read_b128 v[190:193], v171 offset:49152
	ds_read_b128 v[196:199], v171 offset:50176
	ds_read_b128 v[200:203], v171 offset:51200
	ds_read_b128 v[204:207], v171 offset:52224
	ds_read_b128 v[208:211], v171 offset:53248
	ds_read_b128 v[212:215], v171 offset:54272
	ds_read_b128 v[220:223], v171 offset:55296
	ds_read_b128 v[224:227], v171 offset:56320
	s_add_u32 s0, s90, 0x80
	s_addc_u32 s1, s91, 0
	s_add_u32 vcc_lo, s0, 0x100000
	s_addc_u32 vcc_hi, s1, 0
	s_add_i32 m0, s27, 0x18000
	s_nop 0
	global_load_lds_dwordx4 v136, s[0:1]
	s_add_i32 m0, s27, 0x1a000
	s_nop 0
	global_load_lds_dwordx4 v140, s[0:1]
	s_add_i32 m0, s27, 0x1c000
	s_nop 0
	global_load_lds_dwordx4 v136, vcc
	s_add_i32 m0, s27, 0x1e000
	s_nop 0
	global_load_lds_dwordx4 v140, vcc
	s_waitcnt lgkmcnt(0)
	s_setprio 1
	v_mfma_f32_16x16x32_bf16 v[82:85], v[150:153], v[190:193], v[82:85]
	v_mfma_f32_16x16x32_bf16 v[82:85], v[154:157], v[196:199], v[82:85]
	v_mfma_f32_16x16x32_bf16 v[78:81], v[158:161], v[190:193], v[78:81]
	v_mfma_f32_16x16x32_bf16 v[78:81], v[162:165], v[196:199], v[78:81]
	v_mfma_f32_16x16x32_bf16 v[66:69], v[150:153], v[200:203], v[66:69]
	v_mfma_f32_16x16x32_bf16 v[66:69], v[154:157], v[204:207], v[66:69]
	v_mfma_f32_16x16x32_bf16 v[62:65], v[158:161], v[200:203], v[62:65]
	v_mfma_f32_16x16x32_bf16 v[62:65], v[162:165], v[204:207], v[62:65]
	v_mfma_f32_16x16x32_bf16 v[42:45], v[150:153], v[208:211], v[42:45]
	v_mfma_f32_16x16x32_bf16 v[42:45], v[154:157], v[212:215], v[42:45]
	v_mfma_f32_16x16x32_bf16 v[34:37], v[158:161], v[208:211], v[34:37]
	v_mfma_f32_16x16x32_bf16 v[34:37], v[162:165], v[212:215], v[34:37]
	v_mfma_f32_16x16x32_bf16 v[18:21], v[150:153], v[220:223], v[18:21]
	v_mfma_f32_16x16x32_bf16 v[18:21], v[154:157], v[224:227], v[18:21]
	v_mfma_f32_16x16x32_bf16 v[14:17], v[158:161], v[220:223], v[14:17]
	v_mfma_f32_16x16x32_bf16 v[14:17], v[162:165], v[224:227], v[14:17]
	v_mfma_f32_16x16x32_bf16 v[74:77], v[174:177], v[190:193], v[74:77]
	v_mfma_f32_16x16x32_bf16 v[74:77], v[178:181], v[196:199], v[74:77]
	v_mfma_f32_16x16x32_bf16 v[70:73], v[182:185], v[190:193], v[70:73]
	v_mfma_f32_16x16x32_bf16 v[70:73], v[186:189], v[196:199], v[70:73]
	v_mfma_f32_16x16x32_bf16 v[58:61], v[174:177], v[200:203], v[58:61]
	v_mfma_f32_16x16x32_bf16 v[58:61], v[178:181], v[204:207], v[58:61]
	v_mfma_f32_16x16x32_bf16 v[54:57], v[182:185], v[200:203], v[54:57]
	v_mfma_f32_16x16x32_bf16 v[54:57], v[186:189], v[204:207], v[54:57]
	v_mfma_f32_16x16x32_bf16 v[26:29], v[174:177], v[208:211], v[26:29]
	v_mfma_f32_16x16x32_bf16 v[26:29], v[178:181], v[212:215], v[26:29]
	v_mfma_f32_16x16x32_bf16 v[22:25], v[182:185], v[208:211], v[22:25]
	v_mfma_f32_16x16x32_bf16 v[22:25], v[186:189], v[212:215], v[22:25]
	v_mfma_f32_16x16x32_bf16 v[8:11], v[174:177], v[220:223], v[10:13]
	v_mfma_f32_16x16x32_bf16 v[10:13], v[178:181], v[224:227], v[8:11]
	v_mfma_f32_16x16x32_bf16 v[4:7], v[182:185], v[220:223], v[4:7]
	v_mfma_f32_16x16x32_bf16 v[6:9], v[186:189], v[224:227], v[4:7]
	s_setprio 0
	s_waitcnt vmcnt(6)
	s_barrier
	s_add_i32 s23, s23, 2
	s_add_u32 s88, s88, 0x100
	s_addc_u32 s89, s89, 0
	s_add_u32 s9, s9, 0x100
	s_addc_u32 s21, s21, 0
	s_cmp_gt_u32 s23, 61
	s_cbranch_scc0 .LBB0_349
	s_branch .Lip_exit
; #define PG8_STAGE(bufoff, gbase, voff) do { _Pragma("unroll") for (int _i = 0; _i < 2; ++_i) \
;         __builtin_amdgcn_global_load_lds((const unsigned*)((const char*)(gbase) + (voff)[_i]), (PG8_LAS unsigned*)(lds + (bufoff) + ldsw + _i * 8192), 16, 0, 0); } while (0)
; #define PG8_LDA(dst, b, h) do { _Pragma("unroll") for (int m = 0; m < 4; ++m) _Pragma("unroll") for (int k = 0; k < 2; ++k) dst[m][k] = *(const PG8_LAS bf16x8*)(lds + PG8_SA(b, h) + aoff + m * 2048 + k * 1024); } while (0)
; #define PG8_LDB(dst, b, h) do { _Pragma("unroll") for (int n = 0; n < 2; ++n) _Pragma("unroll") for (int k = 0; k < 2; ++k) dst[n][k] = *(const PG8_LAS bf16x8*)(lds + PG8_SB(b, h) + boff + n * 2048 + k * 1024); } while (0)
; #define PG8_MMA(ai, bj, At, Bt) do { __builtin_amdgcn_s_setprio(1); _Pragma("unroll") for (int m = 0; m < 4; ++m) _Pragma("unroll") for (int n = 0; n < 2; ++n) _Pragma("unroll") for (int k = 0; k < 2; ++k) \
;         acc[ai][bj][m][n] = __builtin_amdgcn_mfma_f32_16x16x32_bf16(Bt[n][k], At[m][k], acc[ai][bj][m][n], 0, 0, 0); __builtin_amdgcn_s_setprio(0); } while (0)
; #define PG8_WAIT_V(n) asm volatile("s_waitcnt vmcnt(" #n ")" ::: "memory")
; #define PG8_WAIT_L(n) asm volatile("s_waitcnt lgkmcnt(" #n ")" ::: "memory")
; #define PG8_BAR __builtin_amdgcn_s_barrier()
; #define PG8_SCHED __builtin_amdgcn_sched_barrier(0)
; template <class Epi, class Sched, bool ALIGN_EPI = false, bool SP2 = false>
; __device__ __forceinline__ void gemm_phase(PG8_LAS unsigned char* lds, const Gemm g, const Sched& S, const Epi& E) {
;     ...
;             PG8_LDB(B0, 0, 0); PG8_LDB(B1, 0, 1); PG8_SCHED; PG8_LDA(At, 0, 0); PG8_STAGE(PG8_SA(1, 1), a1 + hstep, voffA);
;             PG8_WAIT_V(8); PG8_WAIT_L(0); PG8_BAR; PG8_MMA(0, 0, At, B0); PG8_MMA(0, 1, At, B1); PG8_BAR; PG8_SCHED;
;             PG8_LDA(At, 0, 1); PG8_STAGE(PG8_SB(0, 0), b2, voffB); PG8_STAGE(PG8_SB(0, 1), b2 + hstep, voffB); PG8_STAGE(PG8_SA(0, 0), a2, voffA);
;             PG8_WAIT_V(8); PG8_WAIT_L(0); PG8_BAR; PG8_MMA(1, 0, At, B0); PG8_MMA(1, 1, At, B1); PG8_BAR; PG8_SCHED;
.Lip_h1:
	ds_read_b128 v[150:153], v169
	ds_read_b128 v[154:157], v169 offset:1024
	ds_read_b128 v[158:161], v169 offset:2048
	ds_read_b128 v[162:165], v169 offset:3072
	ds_read_b128 v[174:177], v170
	ds_read_b128 v[178:181], v170 offset:1024
	ds_read_b128 v[182:185], v170 offset:2048
	ds_read_b128 v[186:189], v170 offset:3072
	s_add_u32 s0, s88, 0xfff00080
	s_addc_u32 s1, s89, -1
	s_cmp_eq_u32 s23, 60
	s_cselect_b32 s93, s51, s1
	s_cselect_b32 s92, s50, s0
	s_cselect_b32 s91, s53, s21
	s_cselect_b32 s90, s52, s9
	ds_read_b128 v[190:193], v171
	ds_read_b128 v[196:199], v171 offset:1024
	ds_read_b128 v[200:203], v171 offset:2048
	ds_read_b128 v[204:207], v171 offset:3072
	ds_read_b128 v[208:211], v171 offset:4096
	ds_read_b128 v[212:215], v171 offset:5120
	ds_read_b128 v[220:223], v171 offset:6144
	ds_read_b128 v[224:227], v171 offset:7168
	s_add_u32 s0, s88, 0xfff00000
	s_addc_u32 s1, s89, -1
	s_add_i32 m0, s27, 0x8000
	s_nop 0
	global_load_lds_dwordx4 v134, s[0:1]
	s_add_i32 m0, s27, 0xa000
	s_nop 0
	global_load_lds_dwordx4 v138, s[0:1]
	s_add_i32 m0, s27, 0xc000
	s_nop 0
	global_load_lds_dwordx4 v134, s[88:89]
	s_add_i32 m0, s27, 0xe000
	s_nop 0
	global_load_lds_dwordx4 v138, s[88:89]
	s_sleep 2
	s_waitcnt lgkmcnt(0)
	s_waitcnt vmcnt(8)
	s_barrier
	s_setprio 2
	v_mfma_f32_16x16x32_bf16 v[38:41], v[150:153], v[190:193], v[38:41]
	v_mfma_f32_16x16x32_bf16 v[38:41], v[154:157], v[196:199], v[38:41]
	v_mfma_f32_16x16x32_bf16 v[30:33], v[158:161], v[190:193], v[30:33]
	v_mfma_f32_16x16x32_bf16 v[30:33], v[162:165], v[196:199], v[30:33]
	v_mfma_f32_16x16x32_bf16 v[50:53], v[174:177], v[190:193], v[50:53]
	v_mfma_f32_16x16x32_bf16 v[50:53], v[178:181], v[196:199], v[50:53]
	v_mfma_f32_16x16x32_bf16 v[46:49], v[182:185], v[190:193], v[46:49]
	v_mfma_f32_16x16x32_bf16 v[46:49], v[186:189], v[196:199], v[46:49]
	v_mfma_f32_16x16x32_bf16 v[118:121], v[182:185], v[200:203], v[118:121]
	v_mfma_f32_16x16x32_bf16 v[118:121], v[186:189], v[204:207], v[118:121]
	v_mfma_f32_16x16x32_bf16 v[122:125], v[174:177], v[200:203], v[122:125]
	v_mfma_f32_16x16x32_bf16 v[122:125], v[178:181], v[204:207], v[122:125]
	v_mfma_f32_16x16x32_bf16 v[126:129], v[158:161], v[200:203], v[126:129]
	v_mfma_f32_16x16x32_bf16 v[126:129], v[162:165], v[204:207], v[126:129]
	v_mfma_f32_16x16x32_bf16 v[130:133], v[150:153], v[200:203], v[130:133]
	v_mfma_f32_16x16x32_bf16 v[130:133], v[154:157], v[204:207], v[130:133]
	v_mfma_f32_16x16x32_bf16 v[114:117], v[150:153], v[208:211], v[114:117]
	v_mfma_f32_16x16x32_bf16 v[114:117], v[154:157], v[212:215], v[114:117]
	v_mfma_f32_16x16x32_bf16 v[110:113], v[158:161], v[208:211], v[110:113]
	v_mfma_f32_16x16x32_bf16 v[110:113], v[162:165], v[212:215], v[110:113]
	v_mfma_f32_16x16x32_bf16 v[106:109], v[174:177], v[208:211], v[106:109]
	v_mfma_f32_16x16x32_bf16 v[106:109], v[178:181], v[212:215], v[106:109]
	v_mfma_f32_16x16x32_bf16 v[102:105], v[182:185], v[208:211], v[102:105]
	v_mfma_f32_16x16x32_bf16 v[102:105], v[186:189], v[212:215], v[102:105]
	v_mfma_f32_16x16x32_bf16 v[86:89], v[182:185], v[220:223], v[86:89]
	v_mfma_f32_16x16x32_bf16 v[86:89], v[186:189], v[224:227], v[86:89]
	v_mfma_f32_16x16x32_bf16 v[90:93], v[174:177], v[220:223], v[90:93]
	v_mfma_f32_16x16x32_bf16 v[90:93], v[178:181], v[224:227], v[90:93]
	v_mfma_f32_16x16x32_bf16 v[94:97], v[158:161], v[220:223], v[94:97]
	v_mfma_f32_16x16x32_bf16 v[94:97], v[162:165], v[224:227], v[94:97]
	v_mfma_f32_16x16x32_bf16 v[98:101], v[150:153], v[220:223], v[98:101]
	v_mfma_f32_16x16x32_bf16 v[98:101], v[154:157], v[224:227], v[98:101]
	s_setprio 0
	ds_read_b128 v[190:193], v171 offset:16384
	ds_read_b128 v[196:199], v171 offset:17408
	ds_read_b128 v[200:203], v171 offset:18432
	ds_read_b128 v[204:207], v171 offset:19456
	ds_read_b128 v[208:211], v171 offset:20480
	ds_read_b128 v[212:215], v171 offset:21504
	ds_read_b128 v[220:223], v171 offset:22528
	ds_read_b128 v[224:227], v171 offset:23552
	s_add_u32 vcc_lo, s90, 0x100000
	s_addc_u32 vcc_hi, s91, 0
	s_add_i32 m0, s27, 0x10000
	s_nop 0
	global_load_lds_dwordx4 v136, s[90:91]
	s_add_i32 m0, s27, 0x12000
	s_nop 0
	global_load_lds_dwordx4 v140, s[90:91]
	s_add_i32 m0, s27, 0x14000
	s_nop 0
	global_load_lds_dwordx4 v136, vcc
	s_add_i32 m0, s27, 0x16000
	s_nop 0
	global_load_lds_dwordx4 v140, vcc
	s_sleep 2
	s_waitcnt lgkmcnt(0)
	s_waitcnt vmcnt(6)
	s_barrier
; #define PG8_STAGE(bufoff, gbase, voff) do { _Pragma("unroll") for (int _i = 0; _i < 2; ++_i) \
;         __builtin_amdgcn_global_load_lds((const unsigned*)((const char*)(gbase) + (voff)[_i]), (PG8_LAS unsigned*)(lds + (bufoff) + ldsw + _i * 8192), 16, 0, 0); } while (0)
; #define PG8_LDA(dst, b, h) do { _Pragma("unroll") for (int m = 0; m < 4; ++m) _Pragma("unroll") for (int k = 0; k < 2; ++k) dst[m][k] = *(const PG8_LAS bf16x8*)(lds + PG8_SA(b, h) + aoff + m * 2048 + k * 1024); } while (0)
; #define PG8_LDB(dst, b, h) do { _Pragma("unroll") for (int n = 0; n < 2; ++n) _Pragma("unroll") for (int k = 0; k < 2; ++k) dst[n][k] = *(const PG8_LAS bf16x8*)(lds + PG8_SB(b, h) + boff + n * 2048 + k * 1024); } while (0)
; #define PG8_MMA(ai, bj, At, Bt) do { __builtin_amdgcn_s_setprio(1); _Pragma("unroll") for (int m = 0; m < 4; ++m) _Pragma("unroll") for (int n = 0; n < 2; ++n) _Pragma("unroll") for (int k = 0; k < 2; ++k) \
;         acc[ai][bj][m][n] = __builtin_amdgcn_mfma_f32_16x16x32_bf16(Bt[n][k], At[m][k], acc[ai][bj][m][n], 0, 0, 0); __builtin_amdgcn_s_setprio(0); } while (0)
; #define PG8_WAIT_V(n) asm volatile("s_waitcnt vmcnt(" #n ")" ::: "memory")
; #define PG8_WAIT_L(n) asm volatile("s_waitcnt lgkmcnt(" #n ")" ::: "memory")
; #define PG8_BAR __builtin_amdgcn_s_barrier()
; #define PG8_SCHED __builtin_amdgcn_sched_barrier(0)
; template <class Epi, class Sched, bool ALIGN_EPI = false, bool SP2 = false>
; __device__ __forceinline__ void gemm_phase(PG8_LAS unsigned char* lds, const Gemm g, const Sched& S, const Epi& E) {
;     ...
;             PG8_WAIT_V(8); PG8_WAIT_L(0); PG8_BAR; PG8_MMA(1, 0, At, B0); PG8_MMA(1, 1, At, B1); PG8_BAR; PG8_SCHED;
;             PG8_LDB(B0, 1, 0); PG8_LDB(B1, 1, 1); PG8_SCHED; PG8_LDA(At, 1, 0); PG8_STAGE(PG8_SA(0, 1), a2 + hstep, voffA);
;             PG8_WAIT_V(8); PG8_WAIT_L(0); PG8_BAR; PG8_MMA(0, 0, At, B0); PG8_MMA(0, 1, At, B1); PG8_BAR; PG8_SCHED;
	s_setprio 2
	v_mfma_f32_16x16x32_bf16 v[82:85], v[150:153], v[190:193], v[82:85]
	v_mfma_f32_16x16x32_bf16 v[82:85], v[154:157], v[196:199], v[82:85]
	v_mfma_f32_16x16x32_bf16 v[78:81], v[158:161], v[190:193], v[78:81]
	v_mfma_f32_16x16x32_bf16 v[78:81], v[162:165], v[196:199], v[78:81]
	v_mfma_f32_16x16x32_bf16 v[74:77], v[174:177], v[190:193], v[74:77]
	v_mfma_f32_16x16x32_bf16 v[74:77], v[178:181], v[196:199], v[74:77]
	v_mfma_f32_16x16x32_bf16 v[70:73], v[182:185], v[190:193], v[70:73]
	v_mfma_f32_16x16x32_bf16 v[70:73], v[186:189], v[196:199], v[70:73]
	v_mfma_f32_16x16x32_bf16 v[54:57], v[182:185], v[200:203], v[54:57]
	v_mfma_f32_16x16x32_bf16 v[54:57], v[186:189], v[204:207], v[54:57]
	v_mfma_f32_16x16x32_bf16 v[58:61], v[174:177], v[200:203], v[58:61]
	v_mfma_f32_16x16x32_bf16 v[58:61], v[178:181], v[204:207], v[58:61]
	v_mfma_f32_16x16x32_bf16 v[62:65], v[158:161], v[200:203], v[62:65]
	v_mfma_f32_16x16x32_bf16 v[62:65], v[162:165], v[204:207], v[62:65]
	v_mfma_f32_16x16x32_bf16 v[66:69], v[150:153], v[200:203], v[66:69]
	v_mfma_f32_16x16x32_bf16 v[66:69], v[154:157], v[204:207], v[66:69]
	v_mfma_f32_16x16x32_bf16 v[42:45], v[150:153], v[208:211], v[42:45]
	v_mfma_f32_16x16x32_bf16 v[42:45], v[154:157], v[212:215], v[42:45]
	v_mfma_f32_16x16x32_bf16 v[34:37], v[158:161], v[208:211], v[34:37]
	v_mfma_f32_16x16x32_bf16 v[34:37], v[162:165], v[212:215], v[34:37]
	v_mfma_f32_16x16x32_bf16 v[26:29], v[174:177], v[208:211], v[26:29]
	v_mfma_f32_16x16x32_bf16 v[26:29], v[178:181], v[212:215], v[26:29]
	v_mfma_f32_16x16x32_bf16 v[22:25], v[182:185], v[208:211], v[22:25]
	v_mfma_f32_16x16x32_bf16 v[22:25], v[186:189], v[212:215], v[22:25]
	v_mfma_f32_16x16x32_bf16 v[4:7], v[182:185], v[220:223], v[6:9]
	v_mfma_f32_16x16x32_bf16 v[4:7], v[186:189], v[224:227], v[4:7]
	v_mfma_f32_16x16x32_bf16 v[10:13], v[174:177], v[220:223], v[10:13]
	v_mfma_f32_16x16x32_bf16 v[10:13], v[178:181], v[224:227], v[10:13]
	v_mfma_f32_16x16x32_bf16 v[14:17], v[158:161], v[220:223], v[14:17]
	v_mfma_f32_16x16x32_bf16 v[14:17], v[162:165], v[224:227], v[14:17]
	v_mfma_f32_16x16x32_bf16 v[18:21], v[150:153], v[220:223], v[18:21]
	v_mfma_f32_16x16x32_bf16 v[18:21], v[154:157], v[224:227], v[18:21]
	s_setprio 0
	s_add_i32 s0, 0, 0x18000
	v_add_u32_e32 v3, s0, v167
	s_add_i32 s1, 0, 0x1c000
	ds_read_b128 v[150:153], v3
	ds_read_b128 v[154:157], v3 offset:1024
	ds_read_b128 v[158:161], v3 offset:2048
	ds_read_b128 v[162:165], v3 offset:3072
	v_add_u32_e32 v3, s1, v167
	ds_read_b128 v[174:177], v3
	ds_read_b128 v[178:181], v3 offset:1024
	ds_read_b128 v[182:185], v3 offset:2048
	ds_read_b128 v[186:189], v3 offset:3072
	ds_read_b128 v[190:193], v171 offset:32768
	ds_read_b128 v[196:199], v171 offset:33792
	ds_read_b128 v[200:203], v171 offset:34816
	ds_read_b128 v[204:207], v171 offset:35840
	ds_read_b128 v[208:211], v171 offset:36864
	ds_read_b128 v[212:215], v171 offset:37888
	ds_read_b128 v[220:223], v171 offset:38912
	ds_read_b128 v[224:227], v171 offset:39936
	s_add_u32 vcc_lo, s92, 0x100000
	s_addc_u32 vcc_hi, s93, 0
	s_mov_b32 m0, s27
	s_nop 0
	global_load_lds_dwordx4 v134, s[92:93]
	s_add_i32 m0, s27, 0x2000
	s_nop 0
	global_load_lds_dwordx4 v138, s[92:93]
	s_add_i32 m0, s27, 0x4000
	s_nop 0
	global_load_lds_dwordx4 v134, vcc
	s_add_i32 m0, s27, 0x6000
	s_nop 0
	global_load_lds_dwordx4 v138, vcc
	s_sleep 2
	s_waitcnt lgkmcnt(0)
	s_waitcnt vmcnt(8)
	s_barrier
; #define PG8_STAGE(bufoff, gbase, voff) do { _Pragma("unroll") for (int _i = 0; _i < 2; ++_i) \
;         __builtin_amdgcn_global_load_lds((const unsigned*)((const char*)(gbase) + (voff)[_i]), (PG8_LAS unsigned*)(lds + (bufoff) + ldsw + _i * 8192), 16, 0, 0); } while (0)
; #define PG8_LDA(dst, b, h) do { _Pragma("unroll") for (int m = 0; m < 4; ++m) _Pragma("unroll") for (int k = 0; k < 2; ++k) dst[m][k] = *(const PG8_LAS bf16x8*)(lds + PG8_SA(b, h) + aoff + m * 2048 + k * 1024); } while (0)
; #define PG8_MMA(ai, bj, At, Bt) do { __builtin_amdgcn_s_setprio(1); _Pragma("unroll") for (int m = 0; m < 4; ++m) _Pragma("unroll") for (int n = 0; n < 2; ++n) _Pragma("unroll") for (int k = 0; k < 2; ++k) \
;         acc[ai][bj][m][n] = __builtin_amdgcn_mfma_f32_16x16x32_bf16(Bt[n][k], At[m][k], acc[ai][bj][m][n], 0, 0, 0); __builtin_amdgcn_s_setprio(0); } while (0)
; #define PG8_WAIT_V(n) asm volatile("s_waitcnt vmcnt(" #n ")" ::: "memory")
; #define PG8_WAIT_L(n) asm volatile("s_waitcnt lgkmcnt(" #n ")" ::: "memory")
; #define PG8_BAR __builtin_amdgcn_s_barrier()
; #define PG8_SCHED __builtin_amdgcn_sched_barrier(0)
; template <class Epi, class Sched, bool ALIGN_EPI = false, bool SP2 = false>
; __device__ __forceinline__ void gemm_phase(PG8_LAS unsigned char* lds, const Gemm g, const Sched& S, const Epi& E) {
;     ...
;             PG8_WAIT_V(8); PG8_WAIT_L(0); PG8_BAR; PG8_MMA(0, 0, At, B0); PG8_MMA(0, 1, At, B1); PG8_BAR; PG8_SCHED;
;             PG8_LDA(At, 1, 1); PG8_STAGE(PG8_SB(1, 0), b3, voffB); PG8_STAGE(PG8_SB(1, 1), b3 + hstep, voffB); PG8_STAGE(PG8_SA(1, 0), a3, voffA);
;             PG8_WAIT_V(8); PG8_WAIT_L(0); PG8_BAR; PG8_MMA(1, 0, At, B0); PG8_MMA(1, 1, At, B1); PG8_BAR; PG8_SCHED;
	s_setprio 2
	v_mfma_f32_16x16x32_bf16 v[38:41], v[150:153], v[190:193], v[38:41]
	v_mfma_f32_16x16x32_bf16 v[38:41], v[154:157], v[196:199], v[38:41]
	v_mfma_f32_16x16x32_bf16 v[30:33], v[158:161], v[190:193], v[30:33]
	v_mfma_f32_16x16x32_bf16 v[30:33], v[162:165], v[196:199], v[30:33]
	v_mfma_f32_16x16x32_bf16 v[50:53], v[174:177], v[190:193], v[50:53]
	v_mfma_f32_16x16x32_bf16 v[50:53], v[178:181], v[196:199], v[50:53]
	v_mfma_f32_16x16x32_bf16 v[46:49], v[182:185], v[190:193], v[46:49]
	v_mfma_f32_16x16x32_bf16 v[46:49], v[186:189], v[196:199], v[46:49]
	v_mfma_f32_16x16x32_bf16 v[118:121], v[182:185], v[200:203], v[118:121]
	v_mfma_f32_16x16x32_bf16 v[118:121], v[186:189], v[204:207], v[118:121]
	v_mfma_f32_16x16x32_bf16 v[122:125], v[174:177], v[200:203], v[122:125]
	v_mfma_f32_16x16x32_bf16 v[122:125], v[178:181], v[204:207], v[122:125]
	v_mfma_f32_16x16x32_bf16 v[126:129], v[158:161], v[200:203], v[126:129]
	v_mfma_f32_16x16x32_bf16 v[126:129], v[162:165], v[204:207], v[126:129]
	v_mfma_f32_16x16x32_bf16 v[130:133], v[150:153], v[200:203], v[130:133]
	v_mfma_f32_16x16x32_bf16 v[130:133], v[154:157], v[204:207], v[130:133]
	v_mfma_f32_16x16x32_bf16 v[114:117], v[150:153], v[208:211], v[114:117]
	v_mfma_f32_16x16x32_bf16 v[114:117], v[154:157], v[212:215], v[114:117]
	v_mfma_f32_16x16x32_bf16 v[110:113], v[158:161], v[208:211], v[110:113]
	v_mfma_f32_16x16x32_bf16 v[110:113], v[162:165], v[212:215], v[110:113]
	v_mfma_f32_16x16x32_bf16 v[106:109], v[174:177], v[208:211], v[106:109]
	v_mfma_f32_16x16x32_bf16 v[106:109], v[178:181], v[212:215], v[106:109]
	v_mfma_f32_16x16x32_bf16 v[102:105], v[182:185], v[208:211], v[102:105]
	v_mfma_f32_16x16x32_bf16 v[102:105], v[186:189], v[212:215], v[102:105]
	v_mfma_f32_16x16x32_bf16 v[86:89], v[182:185], v[220:223], v[86:89]
	v_mfma_f32_16x16x32_bf16 v[86:89], v[186:189], v[224:227], v[86:89]
	v_mfma_f32_16x16x32_bf16 v[90:93], v[174:177], v[220:223], v[90:93]
	v_mfma_f32_16x16x32_bf16 v[90:93], v[178:181], v[224:227], v[90:93]
	v_mfma_f32_16x16x32_bf16 v[94:97], v[158:161], v[220:223], v[94:97]
	v_mfma_f32_16x16x32_bf16 v[94:97], v[162:165], v[224:227], v[94:97]
	v_mfma_f32_16x16x32_bf16 v[98:101], v[150:153], v[220:223], v[98:101]
	v_mfma_f32_16x16x32_bf16 v[98:101], v[154:157], v[224:227], v[98:101]
	s_setprio 0
	ds_read_b128 v[190:193], v171 offset:49152
	ds_read_b128 v[196:199], v171 offset:50176
	ds_read_b128 v[200:203], v171 offset:51200
	ds_read_b128 v[204:207], v171 offset:52224
	ds_read_b128 v[208:211], v171 offset:53248
	ds_read_b128 v[212:215], v171 offset:54272
	ds_read_b128 v[220:223], v171 offset:55296
	ds_read_b128 v[224:227], v171 offset:56320
	s_add_u32 s0, s90, 0x80
	s_addc_u32 s1, s91, 0
	s_add_u32 vcc_lo, s0, 0x100000
	s_addc_u32 vcc_hi, s1, 0
	s_add_i32 m0, s27, 0x18000
	s_nop 0
	global_load_lds_dwordx4 v136, s[0:1]
	s_add_i32 m0, s27, 0x1a000
	s_nop 0
	global_load_lds_dwordx4 v140, s[0:1]
	s_add_i32 m0, s27, 0x1c000
	s_nop 0
	global_load_lds_dwordx4 v136, vcc
	s_add_i32 m0, s27, 0x1e000
	s_nop 0
	global_load_lds_dwordx4 v140, vcc
	s_sleep 2
	s_waitcnt lgkmcnt(0)
	s_waitcnt vmcnt(6)
	s_barrier
	s_setprio 2
	v_mfma_f32_16x16x32_bf16 v[82:85], v[150:153], v[190:193], v[82:85]
	v_mfma_f32_16x16x32_bf16 v[82:85], v[154:157], v[196:199], v[82:85]
	v_mfma_f32_16x16x32_bf16 v[78:81], v[158:161], v[190:193], v[78:81]
	v_mfma_f32_16x16x32_bf16 v[78:81], v[162:165], v[196:199], v[78:81]
	v_mfma_f32_16x16x32_bf16 v[66:69], v[150:153], v[200:203], v[66:69]
	v_mfma_f32_16x16x32_bf16 v[66:69], v[154:157], v[204:207], v[66:69]
	v_mfma_f32_16x16x32_bf16 v[62:65], v[158:161], v[200:203], v[62:65]
	v_mfma_f32_16x16x32_bf16 v[62:65], v[162:165], v[204:207], v[62:65]
	v_mfma_f32_16x16x32_bf16 v[42:45], v[150:153], v[208:211], v[42:45]
	v_mfma_f32_16x16x32_bf16 v[42:45], v[154:157], v[212:215], v[42:45]
	v_mfma_f32_16x16x32_bf16 v[34:37], v[158:161], v[208:211], v[34:37]
	v_mfma_f32_16x16x32_bf16 v[34:37], v[162:165], v[212:215], v[34:37]
	v_mfma_f32_16x16x32_bf16 v[18:21], v[150:153], v[220:223], v[18:21]
	v_mfma_f32_16x16x32_bf16 v[18:21], v[154:157], v[224:227], v[18:21]
	v_mfma_f32_16x16x32_bf16 v[14:17], v[158:161], v[220:223], v[14:17]
	v_mfma_f32_16x16x32_bf16 v[14:17], v[162:165], v[224:227], v[14:17]
	v_mfma_f32_16x16x32_bf16 v[74:77], v[174:177], v[190:193], v[74:77]
	v_mfma_f32_16x16x32_bf16 v[74:77], v[178:181], v[196:199], v[74:77]
	v_mfma_f32_16x16x32_bf16 v[70:73], v[182:185], v[190:193], v[70:73]
	v_mfma_f32_16x16x32_bf16 v[70:73], v[186:189], v[196:199], v[70:73]
	v_mfma_f32_16x16x32_bf16 v[58:61], v[174:177], v[200:203], v[58:61]
	v_mfma_f32_16x16x32_bf16 v[58:61], v[178:181], v[204:207], v[58:61]
	v_mfma_f32_16x16x32_bf16 v[54:57], v[182:185], v[200:203], v[54:57]
	v_mfma_f32_16x16x32_bf16 v[54:57], v[186:189], v[204:207], v[54:57]
	v_mfma_f32_16x16x32_bf16 v[26:29], v[174:177], v[208:211], v[26:29]
	v_mfma_f32_16x16x32_bf16 v[26:29], v[178:181], v[212:215], v[26:29]
	v_mfma_f32_16x16x32_bf16 v[22:25], v[182:185], v[208:211], v[22:25]
	v_mfma_f32_16x16x32_bf16 v[22:25], v[186:189], v[212:215], v[22:25]
	v_mfma_f32_16x16x32_bf16 v[8:11], v[174:177], v[220:223], v[10:13]
	v_mfma_f32_16x16x32_bf16 v[10:13], v[178:181], v[224:227], v[8:11]
	v_mfma_f32_16x16x32_bf16 v[4:7], v[182:185], v[220:223], v[4:7]
	v_mfma_f32_16x16x32_bf16 v[6:9], v[186:189], v[224:227], v[4:7]
	s_setprio 0
	s_add_i32 s23, s23, 2
	s_add_u32 s88, s88, 0x100
	s_addc_u32 s89, s89, 0
	s_add_u32 s9, s9, 0x100
	s_addc_u32 s21, s21, 0
	s_cmp_gt_u32 s23, 61
	s_cbranch_scc0 .Lip_h1

; #define PG8_STAGE(bufoff, gbase, voff) do { _Pragma("unroll") for (int _i = 0; _i < 2; ++_i) \
;         __builtin_amdgcn_global_load_lds((const unsigned*)((const char*)(gbase) + (voff)[_i]), (PG8_LAS unsigned*)(lds + (bufoff) + ldsw + _i * 8192), 16, 0, 0); } while (0)
; #define PG8_LDA(dst, b, h) do { _Pragma("unroll") for (int m = 0; m < 4; ++m) _Pragma("unroll") for (int k = 0; k < 2; ++k) dst[m][k] = *(const PG8_LAS bf16x8*)(lds + PG8_SA(b, h) + aoff + m * 2048 + k * 1024); } while (0)
; #define PG8_LDB(dst, b, h) do { _Pragma("unroll") for (int n = 0; n < 2; ++n) _Pragma("unroll") for (int k = 0; k < 2; ++k) dst[n][k] = *(const PG8_LAS bf16x8*)(lds + PG8_SB(b, h) + boff + n * 2048 + k * 1024); } while (0)
; #define PG8_MMA(ai, bj, At, Bt) do { __builtin_amdgcn_s_setprio(1); _Pragma("unroll") for (int m = 0; m < 4; ++m) _Pragma("unroll") for (int n = 0; n < 2; ++n) _Pragma("unroll") for (int k = 0; k < 2; ++k) \
;         acc[ai][bj][m][n] = __builtin_amdgcn_mfma_f32_16x16x32_bf16(Bt[n][k], At[m][k], acc[ai][bj][m][n], 0, 0, 0); __builtin_amdgcn_s_setprio(0); } while (0)
; #define PG8_WAIT_V(n) asm volatile("s_waitcnt vmcnt(" #n ")" ::: "memory")
; #define PG8_WAIT_L(n) asm volatile("s_waitcnt lgkmcnt(" #n ")" ::: "memory")
; #define PG8_BAR __builtin_amdgcn_s_barrier()
; #define PG8_SCHED __builtin_amdgcn_sched_barrier(0)
; template <class Epi, class Sched, bool ALIGN_EPI = false, bool SP2 = false>
; __device__ __forceinline__ void gemm_phase(PG8_LAS unsigned char* lds, const Gemm g, const Sched& S, const Epi& E) {
;     ...
;             PG8_LDB(B0, 0, 0); PG8_LDB(B1, 0, 1); PG8_SCHED; PG8_LDA(At, 0, 0); PG8_STAGE(PG8_SA(1, 1), a1 + hstep, voffA);
;             PG8_WAIT_V(8); PG8_WAIT_L(0); PG8_BAR; PG8_MMA(0, 0, At, B0); PG8_MMA(0, 1, At, B1); PG8_BAR; PG8_SCHED;
;             PG8_LDA(At, 0, 1); PG8_STAGE(PG8_SB(0, 0), b2, voffB); PG8_STAGE(PG8_SB(0, 1), b2 + hstep, voffB); PG8_STAGE(PG8_SA(0, 0), a2, voffA);
;             PG8_WAIT_V(8); PG8_WAIT_L(0); PG8_BAR; PG8_MMA(1, 0, At, B0); PG8_MMA(1, 1, At, B1); PG8_BAR; PG8_SCHED;
.LBB0_911:
	v_add_u32_e32 v3, s83, v219
	ds_read_b128 v[98:101], v3
	ds_read_b128 v[102:105], v3 offset:1024
	ds_read_b128 v[106:109], v3 offset:2048
	ds_read_b128 v[166:169], v3 offset:3072
	v_add_u32_e32 v3, s86, v219
	s_add_u32 s62, s58, s60
	ds_read_b128 v[170:173], v3
	ds_read_b128 v[174:177], v3 offset:1024
	ds_read_b128 v[178:181], v3 offset:2048
	ds_read_b128 v[182:185], v3 offset:3072
	s_addc_u32 s63, s59, s61
	s_add_u32 s62, s62, 0x100
	s_addc_u32 s63, s63, 0
	s_add_u32 s93, s90, s60
	s_addc_u32 s94, s91, s61
	s_cmpk_eq_i32 s60, 0x1f00
	s_cselect_b32 s65, s19, s63
	s_cselect_b32 s64, s21, s62
	s_cselect_b32 s63, s53, s94
	s_cselect_b32 s62, s57, s93
	v_lshl_add_u64 v[4:5], v[94:95], 0, s[60:61]
	s_add_i32 m0, s24, 0xc000
	ds_read_b128 v[186:189], v244
	ds_read_b128 v[190:193], v244 offset:1024
	ds_read_b128 v[196:199], v244 offset:2048
	ds_read_b128 v[200:203], v244 offset:3072
	ds_read_b128 v[204:207], v244 offset:4096
	ds_read_b128 v[208:211], v244 offset:5120
	ds_read_b128 v[212:215], v244 offset:6144
	ds_read_b128 v[246:249], v244 offset:7168
	global_load_lds_dwordx4 v[4:5], off
	v_lshl_add_u64 v[4:5], v[96:97], 0, s[60:61]
	s_add_i32 m0, s24, 0xe000
	s_nop 0
	global_load_lds_dwordx4 v[4:5], off
	s_waitcnt vmcnt(8)
	s_waitcnt lgkmcnt(0)
	s_barrier
	s_setprio 1
	s_waitcnt lgkmcnt(0)
	v_mfma_f32_16x16x32_bf16 v[146:149], v[98:101], v[186:189], v[146:149]
	v_mfma_f32_16x16x32_bf16 v[146:149], v[102:105], v[190:193], v[146:149]
	v_mfma_f32_16x16x32_bf16 v[142:145], v[106:109], v[186:189], v[142:145]
	v_mfma_f32_16x16x32_bf16 v[142:145], v[166:169], v[190:193], v[142:145]
	v_mfma_f32_16x16x32_bf16 v[66:69], v[170:173], v[186:189], v[66:69]
	v_mfma_f32_16x16x32_bf16 v[66:69], v[174:177], v[190:193], v[66:69]
	v_mfma_f32_16x16x32_bf16 v[62:65], v[178:181], v[186:189], v[62:65]
	v_mfma_f32_16x16x32_bf16 v[62:65], v[182:185], v[190:193], v[62:65]
	v_mfma_f32_16x16x32_bf16 v[54:57], v[178:181], v[196:199], v[54:57]
	v_mfma_f32_16x16x32_bf16 v[54:57], v[182:185], v[200:203], v[54:57]
	v_mfma_f32_16x16x32_bf16 v[58:61], v[170:173], v[196:199], v[58:61]
	v_mfma_f32_16x16x32_bf16 v[58:61], v[174:177], v[200:203], v[58:61]
	v_mfma_f32_16x16x32_bf16 v[134:137], v[106:109], v[196:199], v[134:137]
	v_mfma_f32_16x16x32_bf16 v[134:137], v[166:169], v[200:203], v[134:137]
	v_mfma_f32_16x16x32_bf16 v[138:141], v[98:101], v[196:199], v[138:141]
	v_mfma_f32_16x16x32_bf16 v[138:141], v[102:105], v[200:203], v[138:141]
	s_setprio 0
	s_setprio 1
	v_mfma_f32_16x16x32_bf16 v[130:133], v[98:101], v[204:207], v[130:133]
	v_mfma_f32_16x16x32_bf16 v[130:133], v[102:105], v[208:211], v[130:133]
	v_mfma_f32_16x16x32_bf16 v[126:129], v[106:109], v[204:207], v[126:129]
	v_mfma_f32_16x16x32_bf16 v[126:129], v[166:169], v[208:211], v[126:129]
	v_mfma_f32_16x16x32_bf16 v[50:53], v[170:173], v[204:207], v[50:53]
	v_mfma_f32_16x16x32_bf16 v[50:53], v[174:177], v[208:211], v[50:53]
	v_mfma_f32_16x16x32_bf16 v[46:49], v[178:181], v[204:207], v[46:49]
	v_mfma_f32_16x16x32_bf16 v[46:49], v[182:185], v[208:211], v[46:49]
	v_mfma_f32_16x16x32_bf16 v[38:41], v[178:181], v[212:215], v[38:41]
	v_mfma_f32_16x16x32_bf16 v[38:41], v[182:185], v[246:249], v[38:41]
	v_mfma_f32_16x16x32_bf16 v[42:45], v[170:173], v[212:215], v[42:45]
	v_mfma_f32_16x16x32_bf16 v[42:45], v[174:177], v[246:249], v[42:45]
	v_mfma_f32_16x16x32_bf16 v[118:121], v[106:109], v[212:215], v[118:121]
	v_mfma_f32_16x16x32_bf16 v[118:121], v[166:169], v[246:249], v[118:121]
	v_mfma_f32_16x16x32_bf16 v[122:125], v[98:101], v[212:215], v[122:125]
	v_mfma_f32_16x16x32_bf16 v[122:125], v[102:105], v[246:249], v[122:125]
	s_setprio 0
	s_barrier
	s_add_i32 s93, s83, s2
	v_lshl_add_u64 v[216:217], s[62:63], 0, v[152:153]
	s_mov_b32 m0, s93
	ds_read_b128 v[186:189], v244 offset:16384
	ds_read_b128 v[190:193], v244 offset:17408
	ds_read_b128 v[196:199], v244 offset:18432
	ds_read_b128 v[200:203], v244 offset:19456
	ds_read_b128 v[204:207], v244 offset:20480
	ds_read_b128 v[208:211], v244 offset:21504
	ds_read_b128 v[212:215], v244 offset:22528
	ds_read_b128 v[246:249], v244 offset:23552
	global_load_lds_dwordx4 v[216:217], off
	s_add_i32 m0, s93, 0x2000
	s_add_u32 s94, s62, 0x100000
	v_lshl_add_u64 v[250:251], s[62:63], 0, v[156:157]
	s_addc_u32 s95, s63, 0
	s_add_i32 s93, s86, s2
	global_load_lds_dwordx4 v[250:251], off
	v_lshl_add_u64 v[4:5], s[94:95], 0, v[152:153]
	s_mov_b32 m0, s93
	v_lshl_add_u64 v[252:253], s[64:65], 0, v[150:151]
	global_load_lds_dwordx4 v[4:5], off
	v_lshl_add_u64 v[4:5], s[94:95], 0, v[156:157]
	s_add_i32 m0, s93, 0x2000
	v_lshl_add_u64 v[222:223], s[64:65], 0, v[154:155]
	global_load_lds_dwordx4 v[4:5], off
	s_mov_b32 m0, s24
	s_nop 0
	global_load_lds_dwordx4 v[252:253], off
	s_mov_b32 m0, s25
	s_nop 0
	global_load_lds_dwordx4 v[222:223], off
	s_waitcnt vmcnt(8)
	s_waitcnt lgkmcnt(0)
	s_barrier
; #define PG8_STAGE(bufoff, gbase, voff) do { _Pragma("unroll") for (int _i = 0; _i < 2; ++_i) \
;         __builtin_amdgcn_global_load_lds((const unsigned*)((const char*)(gbase) + (voff)[_i]), (PG8_LAS unsigned*)(lds + (bufoff) + ldsw + _i * 8192), 16, 0, 0); } while (0)
; #define PG8_LDA(dst, b, h) do { _Pragma("unroll") for (int m = 0; m < 4; ++m) _Pragma("unroll") for (int k = 0; k < 2; ++k) dst[m][k] = *(const PG8_LAS bf16x8*)(lds + PG8_SA(b, h) + aoff + m * 2048 + k * 1024); } while (0)
; #define PG8_LDB(dst, b, h) do { _Pragma("unroll") for (int n = 0; n < 2; ++n) _Pragma("unroll") for (int k = 0; k < 2; ++k) dst[n][k] = *(const PG8_LAS bf16x8*)(lds + PG8_SB(b, h) + boff + n * 2048 + k * 1024); } while (0)
; #define PG8_MMA(ai, bj, At, Bt) do { __builtin_amdgcn_s_setprio(1); _Pragma("unroll") for (int m = 0; m < 4; ++m) _Pragma("unroll") for (int n = 0; n < 2; ++n) _Pragma("unroll") for (int k = 0; k < 2; ++k) \
;         acc[ai][bj][m][n] = __builtin_amdgcn_mfma_f32_16x16x32_bf16(Bt[n][k], At[m][k], acc[ai][bj][m][n], 0, 0, 0); __builtin_amdgcn_s_setprio(0); } while (0)
; #define PG8_WAIT_V(n) asm volatile("s_waitcnt vmcnt(" #n ")" ::: "memory")
; #define PG8_WAIT_L(n) asm volatile("s_waitcnt lgkmcnt(" #n ")" ::: "memory")
; #define PG8_BAR __builtin_amdgcn_s_barrier()
; #define PG8_SCHED __builtin_amdgcn_sched_barrier(0)
; template <class Epi, class Sched, bool ALIGN_EPI = false, bool SP2 = false>
; __device__ __forceinline__ void gemm_phase(PG8_LAS unsigned char* lds, const Gemm g, const Sched& S, const Epi& E) {
;     ...
;             PG8_WAIT_V(8); PG8_WAIT_L(0); PG8_BAR; PG8_MMA(1, 0, At, B0); PG8_MMA(1, 1, At, B1); PG8_BAR; PG8_SCHED;
;             PG8_LDB(B0, 1, 0); PG8_LDB(B1, 1, 1); PG8_SCHED; PG8_LDA(At, 1, 0); PG8_STAGE(PG8_SA(0, 1), a2 + hstep, voffA);
;             PG8_WAIT_V(8); PG8_WAIT_L(0); PG8_BAR; PG8_MMA(0, 0, At, B0); PG8_MMA(0, 1, At, B1); PG8_BAR; PG8_SCHED;
	s_setprio 1
	s_waitcnt lgkmcnt(0)
	v_mfma_f32_16x16x32_bf16 v[114:117], v[98:101], v[186:189], v[114:117]
	v_mfma_f32_16x16x32_bf16 v[114:117], v[102:105], v[190:193], v[114:117]
	v_mfma_f32_16x16x32_bf16 v[110:113], v[106:109], v[186:189], v[110:113]
	v_mfma_f32_16x16x32_bf16 v[110:113], v[166:169], v[190:193], v[110:113]
	v_mfma_f32_16x16x32_bf16 v[34:37], v[170:173], v[186:189], v[34:37]
	v_mfma_f32_16x16x32_bf16 v[34:37], v[174:177], v[190:193], v[34:37]
	v_mfma_f32_16x16x32_bf16 v[30:33], v[178:181], v[186:189], v[30:33]
	v_mfma_f32_16x16x32_bf16 v[30:33], v[182:185], v[190:193], v[30:33]
	v_mfma_f32_16x16x32_bf16 v[22:25], v[178:181], v[196:199], v[22:25]
	v_mfma_f32_16x16x32_bf16 v[22:25], v[182:185], v[200:203], v[22:25]
	v_mfma_f32_16x16x32_bf16 v[26:29], v[170:173], v[196:199], v[26:29]
	v_mfma_f32_16x16x32_bf16 v[26:29], v[174:177], v[200:203], v[26:29]
	v_mfma_f32_16x16x32_bf16 v[86:89], v[106:109], v[196:199], v[86:89]
	v_mfma_f32_16x16x32_bf16 v[86:89], v[166:169], v[200:203], v[86:89]
	v_mfma_f32_16x16x32_bf16 v[90:93], v[98:101], v[196:199], v[90:93]
	v_mfma_f32_16x16x32_bf16 v[90:93], v[102:105], v[200:203], v[90:93]
	s_setprio 0
	s_setprio 1
	v_mfma_f32_16x16x32_bf16 v[82:85], v[98:101], v[204:207], v[82:85]
	v_mfma_f32_16x16x32_bf16 v[82:85], v[102:105], v[208:211], v[82:85]
	v_mfma_f32_16x16x32_bf16 v[78:81], v[106:109], v[204:207], v[78:81]
	v_mfma_f32_16x16x32_bf16 v[78:81], v[166:169], v[208:211], v[78:81]
	v_mfma_f32_16x16x32_bf16 v[18:21], v[170:173], v[204:207], v[18:21]
	v_mfma_f32_16x16x32_bf16 v[18:21], v[174:177], v[208:211], v[18:21]
	v_mfma_f32_16x16x32_bf16 v[14:17], v[178:181], v[204:207], v[14:17]
	v_mfma_f32_16x16x32_bf16 v[14:17], v[182:185], v[208:211], v[14:17]
	v_mfma_f32_16x16x32_bf16 v[4:7], v[178:181], v[212:215], v[6:9]
	v_mfma_f32_16x16x32_bf16 v[4:7], v[182:185], v[246:249], v[4:7]
	v_mfma_f32_16x16x32_bf16 v[10:13], v[170:173], v[212:215], v[10:13]
	v_mfma_f32_16x16x32_bf16 v[10:13], v[174:177], v[246:249], v[10:13]
	v_mfma_f32_16x16x32_bf16 v[70:73], v[106:109], v[212:215], v[70:73]
	v_mfma_f32_16x16x32_bf16 v[70:73], v[166:169], v[246:249], v[70:73]
	v_mfma_f32_16x16x32_bf16 v[74:77], v[98:101], v[212:215], v[74:77]
	v_mfma_f32_16x16x32_bf16 v[74:77], v[102:105], v[246:249], v[74:77]
	s_setprio 0
	s_barrier
	s_add_i32 s93, 0, 0x18000
	v_add_u32_e32 v3, s93, v219
	s_add_i32 s94, 0, 0x1c000
	ds_read_b128 v[98:101], v3
	ds_read_b128 v[102:105], v3 offset:1024
	ds_read_b128 v[106:109], v3 offset:2048
	ds_read_b128 v[166:169], v3 offset:3072
	v_add_u32_e32 v3, s94, v219
	ds_read_b128 v[170:173], v3
	ds_read_b128 v[174:177], v3 offset:1024
	ds_read_b128 v[178:181], v3 offset:2048
	ds_read_b128 v[182:185], v3 offset:3072
	s_add_u32 s64, s64, 0x100000
	s_addc_u32 s65, s65, 0
	s_mov_b32 m0, s26
	v_lshl_add_u64 v[8:9], s[64:65], 0, v[150:151]
	ds_read_b128 v[186:189], v244 offset:32768
	ds_read_b128 v[190:193], v244 offset:33792
	ds_read_b128 v[196:199], v244 offset:34816
	ds_read_b128 v[200:203], v244 offset:35840
	ds_read_b128 v[204:207], v244 offset:36864
	ds_read_b128 v[208:211], v244 offset:37888
	ds_read_b128 v[212:215], v244 offset:38912
	ds_read_b128 v[246:249], v244 offset:39936
	global_load_lds_dwordx4 v[8:9], off
	v_lshl_add_u64 v[8:9], s[64:65], 0, v[154:155]
	s_mov_b32 m0, s27
	s_nop 0
	global_load_lds_dwordx4 v[8:9], off
	s_waitcnt vmcnt(8)
	s_waitcnt lgkmcnt(0)
	s_barrier
	s_setprio 1
	s_waitcnt lgkmcnt(0)
	v_mfma_f32_16x16x32_bf16 v[146:149], v[98:101], v[186:189], v[146:149]
	v_mfma_f32_16x16x32_bf16 v[146:149], v[102:105], v[190:193], v[146:149]
	v_mfma_f32_16x16x32_bf16 v[142:145], v[106:109], v[186:189], v[142:145]
	v_mfma_f32_16x16x32_bf16 v[142:145], v[166:169], v[190:193], v[142:145]
	v_mfma_f32_16x16x32_bf16 v[66:69], v[170:173], v[186:189], v[66:69]
	v_mfma_f32_16x16x32_bf16 v[66:69], v[174:177], v[190:193], v[66:69]
	v_mfma_f32_16x16x32_bf16 v[62:65], v[178:181], v[186:189], v[62:65]
	v_mfma_f32_16x16x32_bf16 v[62:65], v[182:185], v[190:193], v[62:65]
	v_mfma_f32_16x16x32_bf16 v[54:57], v[178:181], v[196:199], v[54:57]
	v_mfma_f32_16x16x32_bf16 v[54:57], v[182:185], v[200:203], v[54:57]
	v_mfma_f32_16x16x32_bf16 v[58:61], v[170:173], v[196:199], v[58:61]
	v_mfma_f32_16x16x32_bf16 v[58:61], v[174:177], v[200:203], v[58:61]
	v_mfma_f32_16x16x32_bf16 v[134:137], v[106:109], v[196:199], v[134:137]
	v_mfma_f32_16x16x32_bf16 v[134:137], v[166:169], v[200:203], v[134:137]
	v_mfma_f32_16x16x32_bf16 v[138:141], v[98:101], v[196:199], v[138:141]
	v_mfma_f32_16x16x32_bf16 v[138:141], v[102:105], v[200:203], v[138:141]
	s_setprio 0
	s_setprio 1
	v_mfma_f32_16x16x32_bf16 v[130:133], v[98:101], v[204:207], v[130:133]
	v_mfma_f32_16x16x32_bf16 v[130:133], v[102:105], v[208:211], v[130:133]
	v_mfma_f32_16x16x32_bf16 v[126:129], v[106:109], v[204:207], v[126:129]
	v_mfma_f32_16x16x32_bf16 v[126:129], v[166:169], v[208:211], v[126:129]
	v_mfma_f32_16x16x32_bf16 v[50:53], v[170:173], v[204:207], v[50:53]
	v_mfma_f32_16x16x32_bf16 v[50:53], v[174:177], v[208:211], v[50:53]
	v_mfma_f32_16x16x32_bf16 v[46:49], v[178:181], v[204:207], v[46:49]
	v_mfma_f32_16x16x32_bf16 v[46:49], v[182:185], v[208:211], v[46:49]
	v_mfma_f32_16x16x32_bf16 v[38:41], v[178:181], v[212:215], v[38:41]
	v_mfma_f32_16x16x32_bf16 v[38:41], v[182:185], v[246:249], v[38:41]
	v_mfma_f32_16x16x32_bf16 v[42:45], v[170:173], v[212:215], v[42:45]
	v_mfma_f32_16x16x32_bf16 v[42:45], v[174:177], v[246:249], v[42:45]
	v_mfma_f32_16x16x32_bf16 v[118:121], v[106:109], v[212:215], v[118:121]
	v_mfma_f32_16x16x32_bf16 v[118:121], v[166:169], v[246:249], v[118:121]
	v_mfma_f32_16x16x32_bf16 v[122:125], v[98:101], v[212:215], v[122:125]
	v_mfma_f32_16x16x32_bf16 v[122:125], v[102:105], v[246:249], v[122:125]
	s_setprio 0
	s_barrier
; #define PG8_STAGE(bufoff, gbase, voff) do { _Pragma("unroll") for (int _i = 0; _i < 2; ++_i) \
;         __builtin_amdgcn_global_load_lds((const unsigned*)((const char*)(gbase) + (voff)[_i]), (PG8_LAS unsigned*)(lds + (bufoff) + ldsw + _i * 8192), 16, 0, 0); } while (0)
; #define PG8_LDA(dst, b, h) do { _Pragma("unroll") for (int m = 0; m < 4; ++m) _Pragma("unroll") for (int k = 0; k < 2; ++k) dst[m][k] = *(const PG8_LAS bf16x8*)(lds + PG8_SA(b, h) + aoff + m * 2048 + k * 1024); } while (0)
; #define PG8_MMA(ai, bj, At, Bt) do { __builtin_amdgcn_s_setprio(1); _Pragma("unroll") for (int m = 0; m < 4; ++m) _Pragma("unroll") for (int n = 0; n < 2; ++n) _Pragma("unroll") for (int k = 0; k < 2; ++k) \
;         acc[ai][bj][m][n] = __builtin_amdgcn_mfma_f32_16x16x32_bf16(Bt[n][k], At[m][k], acc[ai][bj][m][n], 0, 0, 0); __builtin_amdgcn_s_setprio(0); } while (0)
; #define PG8_WAIT_V(n) asm volatile("s_waitcnt vmcnt(" #n ")" ::: "memory")
; #define PG8_WAIT_L(n) asm volatile("s_waitcnt lgkmcnt(" #n ")" ::: "memory")
; #define PG8_BAR __builtin_amdgcn_s_barrier()
; #define PG8_SCHED __builtin_amdgcn_sched_barrier(0)
; template <class Epi, class Sched, bool ALIGN_EPI = false, bool SP2 = false>
; __device__ __forceinline__ void gemm_phase(PG8_LAS unsigned char* lds, const Gemm g, const Sched& S, const Epi& E) {
;     ...
;             PG8_LDA(At, 1, 1); PG8_STAGE(PG8_SB(1, 0), b3, voffB); PG8_STAGE(PG8_SB(1, 1), b3 + hstep, voffB); PG8_STAGE(PG8_SA(1, 0), a3, voffA);
;             PG8_WAIT_V(8); PG8_WAIT_L(0); PG8_BAR; PG8_MMA(1, 0, At, B0); PG8_MMA(1, 1, At, B1); PG8_BAR; PG8_SCHED;
	s_add_i32 s64, s93, s2
	v_lshl_add_u64 v[8:9], v[216:217], 0, s[14:15]
	s_mov_b32 m0, s64
	ds_read_b128 v[186:189], v244 offset:49152
	ds_read_b128 v[190:193], v244 offset:50176
	ds_read_b128 v[196:199], v244 offset:51200
	ds_read_b128 v[200:203], v244 offset:52224
	ds_read_b128 v[204:207], v244 offset:53248
	ds_read_b128 v[208:211], v244 offset:54272
	ds_read_b128 v[212:215], v244 offset:55296
	ds_read_b128 v[246:249], v244 offset:56320
	global_load_lds_dwordx4 v[8:9], off
	s_add_i32 m0, s64, 0x2000
	s_add_u32 s62, s62, 0x100080
	v_lshl_add_u64 v[8:9], v[250:251], 0, s[14:15]
	s_addc_u32 s63, s63, 0
	s_add_i32 s64, s94, s2
	global_load_lds_dwordx4 v[8:9], off
	v_lshl_add_u64 v[8:9], s[62:63], 0, v[152:153]
	s_mov_b32 m0, s64
	s_nop 0
	global_load_lds_dwordx4 v[8:9], off
	v_lshl_add_u64 v[8:9], s[62:63], 0, v[156:157]
	s_add_i32 m0, s64, 0x2000
	s_nop 0
	global_load_lds_dwordx4 v[8:9], off
	v_lshl_add_u64 v[8:9], v[252:253], 0, s[14:15]
	s_mov_b32 m0, s66
	s_nop 0
	global_load_lds_dwordx4 v[8:9], off
	v_lshl_add_u64 v[8:9], v[222:223], 0, s[14:15]
	s_mov_b32 m0, s67
	s_nop 0
	global_load_lds_dwordx4 v[8:9], off
	s_waitcnt vmcnt(8)
	s_waitcnt lgkmcnt(0)
	s_barrier
	s_setprio 1
	s_waitcnt lgkmcnt(0)
	v_mfma_f32_16x16x32_bf16 v[114:117], v[98:101], v[186:189], v[114:117]
	v_mfma_f32_16x16x32_bf16 v[114:117], v[102:105], v[190:193], v[114:117]
	v_mfma_f32_16x16x32_bf16 v[110:113], v[106:109], v[186:189], v[110:113]
	v_mfma_f32_16x16x32_bf16 v[110:113], v[166:169], v[190:193], v[110:113]
	v_mfma_f32_16x16x32_bf16 v[90:93], v[98:101], v[196:199], v[90:93]
	v_mfma_f32_16x16x32_bf16 v[90:93], v[102:105], v[200:203], v[90:93]
	v_mfma_f32_16x16x32_bf16 v[86:89], v[106:109], v[196:199], v[86:89]
	v_mfma_f32_16x16x32_bf16 v[86:89], v[166:169], v[200:203], v[86:89]
	v_mfma_f32_16x16x32_bf16 v[82:85], v[98:101], v[204:207], v[82:85]
	v_mfma_f32_16x16x32_bf16 v[82:85], v[102:105], v[208:211], v[82:85]
	v_mfma_f32_16x16x32_bf16 v[78:81], v[106:109], v[204:207], v[78:81]
	v_mfma_f32_16x16x32_bf16 v[78:81], v[166:169], v[208:211], v[78:81]
	v_mfma_f32_16x16x32_bf16 v[74:77], v[98:101], v[212:215], v[74:77]
	v_mfma_f32_16x16x32_bf16 v[74:77], v[102:105], v[246:249], v[74:77]
	v_mfma_f32_16x16x32_bf16 v[70:73], v[106:109], v[212:215], v[70:73]
	v_mfma_f32_16x16x32_bf16 v[70:73], v[166:169], v[246:249], v[70:73]
	s_setprio 0
	s_setprio 1
	v_mfma_f32_16x16x32_bf16 v[34:37], v[170:173], v[186:189], v[34:37]
	v_mfma_f32_16x16x32_bf16 v[34:37], v[174:177], v[190:193], v[34:37]
	v_mfma_f32_16x16x32_bf16 v[30:33], v[178:181], v[186:189], v[30:33]
	v_mfma_f32_16x16x32_bf16 v[30:33], v[182:185], v[190:193], v[30:33]
	v_mfma_f32_16x16x32_bf16 v[26:29], v[170:173], v[196:199], v[26:29]
	v_mfma_f32_16x16x32_bf16 v[26:29], v[174:177], v[200:203], v[26:29]
	v_mfma_f32_16x16x32_bf16 v[22:25], v[178:181], v[196:199], v[22:25]
	v_mfma_f32_16x16x32_bf16 v[22:25], v[182:185], v[200:203], v[22:25]
	v_mfma_f32_16x16x32_bf16 v[18:21], v[170:173], v[204:207], v[18:21]
	v_mfma_f32_16x16x32_bf16 v[18:21], v[174:177], v[208:211], v[18:21]
	v_mfma_f32_16x16x32_bf16 v[14:17], v[178:181], v[204:207], v[14:17]
	v_mfma_f32_16x16x32_bf16 v[14:17], v[182:185], v[208:211], v[14:17]
	v_mfma_f32_16x16x32_bf16 v[8:11], v[170:173], v[212:215], v[10:13]
	v_mfma_f32_16x16x32_bf16 v[10:13], v[174:177], v[246:249], v[8:11]
	v_mfma_f32_16x16x32_bf16 v[4:7], v[178:181], v[212:215], v[4:7]
	v_mfma_f32_16x16x32_bf16 v[6:9], v[182:185], v[246:249], v[4:7]
	s_setprio 0
	s_barrier
	s_add_i32 s92, s92, 2
	s_add_u32 s60, s60, 0x100
	s_addc_u32 s61, s61, 0
	s_cmp_gt_u32 s92, 61
	s_cbranch_scc1 .LBB0_914

; #define PG8_STAGE(bufoff, gbase, voff) do { _Pragma("unroll") for (int _i = 0; _i < 2; ++_i) \
;         __builtin_amdgcn_global_load_lds((const unsigned*)((const char*)(gbase) + (voff)[_i]), (PG8_LAS unsigned*)(lds + (bufoff) + ldsw + _i * 8192), 16, 0, 0); } while (0)
; #define PG8_LDA(dst, b, h) do { _Pragma("unroll") for (int m = 0; m < 4; ++m) _Pragma("unroll") for (int k = 0; k < 2; ++k) dst[m][k] = *(const PG8_LAS bf16x8*)(lds + PG8_SA(b, h) + aoff + m * 2048 + k * 1024); } while (0)
; #define PG8_LDB(dst, b, h) do { _Pragma("unroll") for (int n = 0; n < 2; ++n) _Pragma("unroll") for (int k = 0; k < 2; ++k) dst[n][k] = *(const PG8_LAS bf16x8*)(lds + PG8_SB(b, h) + boff + n * 2048 + k * 1024); } while (0)
; #define PG8_MMA(ai, bj, At, Bt) do { __builtin_amdgcn_s_setprio(1); _Pragma("unroll") for (int m = 0; m < 4; ++m) _Pragma("unroll") for (int n = 0; n < 2; ++n) _Pragma("unroll") for (int k = 0; k < 2; ++k) \
;         acc[ai][bj][m][n] = __builtin_amdgcn_mfma_f32_16x16x32_bf16(Bt[n][k], At[m][k], acc[ai][bj][m][n], 0, 0, 0); __builtin_amdgcn_s_setprio(0); } while (0)
; #define PG8_WAIT_V(n) asm volatile("s_waitcnt vmcnt(" #n ")" ::: "memory")
; #define PG8_WAIT_L(n) asm volatile("s_waitcnt lgkmcnt(" #n ")" ::: "memory")
; #define PG8_BAR __builtin_amdgcn_s_barrier()
; #define PG8_SCHED __builtin_amdgcn_sched_barrier(0)
; template <class Epi, class Sched, bool ALIGN_EPI = false, bool SP2 = false>
; __device__ __forceinline__ void gemm_phase(PG8_LAS unsigned char* lds, const Gemm g, const Sched& S, const Epi& E) {
;     ...
;             PG8_LDB(B0, 0, 0); PG8_LDB(B1, 0, 1); PG8_SCHED; PG8_LDA(At, 0, 0); PG8_STAGE(PG8_SA(1, 1), a1 + hstep, voffA);
;             PG8_WAIT_V(8); PG8_WAIT_L(0); PG8_BAR; PG8_MMA(0, 0, At, B0); PG8_MMA(0, 1, At, B1); PG8_BAR; PG8_SCHED;
;             PG8_LDA(At, 0, 1); PG8_STAGE(PG8_SB(0, 0), b2, voffB); PG8_STAGE(PG8_SB(0, 1), b2 + hstep, voffB); PG8_STAGE(PG8_SA(0, 0), a2, voffA);
;             PG8_WAIT_V(8); PG8_WAIT_L(0); PG8_BAR; PG8_MMA(1, 0, At, B0); PG8_MMA(1, 1, At, B1); PG8_BAR; PG8_SCHED;
.LBB0_1251:
	ds_read_b128 v[130:133], v177
	ds_read_b128 v[134:137], v177 offset:1024
	ds_read_b128 v[138:141], v177 offset:2048
	ds_read_b128 v[142:145], v177 offset:3072
	ds_read_b128 v[162:165], v178
	ds_read_b128 v[180:183], v178 offset:1024
	ds_read_b128 v[184:187], v178 offset:2048
	ds_read_b128 v[188:191], v178 offset:3072
	s_add_u32 s40, s36, 0xfff00080
	s_addc_u32 s41, s37, -1
	s_cmp_eq_u32 s58, 60
	s_cselect_b32 s43, s15, s41
	s_cselect_b32 s42, s17, s40
	s_cselect_b32 s41, s54, s57
	s_cselect_b32 s40, s55, s56
	ds_read_b128 v[196:199], v179
	ds_read_b128 v[200:203], v179 offset:1024
	ds_read_b128 v[204:207], v179 offset:2048
	ds_read_b128 v[208:211], v179 offset:3072
	ds_read_b128 v[212:215], v179 offset:4096
	ds_read_b128 v[220:223], v179 offset:5120
	ds_read_b128 v[224:227], v179 offset:6144
	ds_read_b128 v[228:231], v179 offset:7168
	s_add_i32 m0, s24, 0xc000
	s_nop 0
	global_load_lds_dwordx4 v146, s[36:37]
	s_add_i32 m0, s24, 0xe000
	s_nop 0
	global_load_lds_dwordx4 v150, s[36:37]
	s_waitcnt lgkmcnt(0)
	s_setprio 1
	v_mfma_f32_16x16x32_bf16 v[126:129], v[130:133], v[196:199], v[126:129]
	v_mfma_f32_16x16x32_bf16 v[126:129], v[134:137], v[200:203], v[126:129]
	v_mfma_f32_16x16x32_bf16 v[122:125], v[138:141], v[196:199], v[122:125]
	v_mfma_f32_16x16x32_bf16 v[122:125], v[142:145], v[200:203], v[122:125]
	v_mfma_f32_16x16x32_bf16 v[118:121], v[162:165], v[196:199], v[118:121]
	v_mfma_f32_16x16x32_bf16 v[118:121], v[180:183], v[200:203], v[118:121]
	v_mfma_f32_16x16x32_bf16 v[114:117], v[184:187], v[196:199], v[114:117]
	v_mfma_f32_16x16x32_bf16 v[114:117], v[188:191], v[200:203], v[114:117]
	v_mfma_f32_16x16x32_bf16 v[98:101], v[184:187], v[204:207], v[98:101]
	v_mfma_f32_16x16x32_bf16 v[98:101], v[188:191], v[208:211], v[98:101]
	v_mfma_f32_16x16x32_bf16 v[102:105], v[162:165], v[204:207], v[102:105]
	v_mfma_f32_16x16x32_bf16 v[102:105], v[180:183], v[208:211], v[102:105]
	v_mfma_f32_16x16x32_bf16 v[106:109], v[138:141], v[204:207], v[106:109]
	v_mfma_f32_16x16x32_bf16 v[106:109], v[142:145], v[208:211], v[106:109]
	v_mfma_f32_16x16x32_bf16 v[110:113], v[130:133], v[204:207], v[110:113]
	v_mfma_f32_16x16x32_bf16 v[110:113], v[134:137], v[208:211], v[110:113]
	v_mfma_f32_16x16x32_bf16 v[94:97], v[130:133], v[212:215], v[94:97]
	v_mfma_f32_16x16x32_bf16 v[94:97], v[134:137], v[220:223], v[94:97]
	v_mfma_f32_16x16x32_bf16 v[90:93], v[138:141], v[212:215], v[90:93]
	v_mfma_f32_16x16x32_bf16 v[90:93], v[142:145], v[220:223], v[90:93]
	v_mfma_f32_16x16x32_bf16 v[86:89], v[162:165], v[212:215], v[86:89]
	v_mfma_f32_16x16x32_bf16 v[86:89], v[180:183], v[220:223], v[86:89]
	v_mfma_f32_16x16x32_bf16 v[82:85], v[184:187], v[212:215], v[82:85]
	v_mfma_f32_16x16x32_bf16 v[82:85], v[188:191], v[220:223], v[82:85]
	v_mfma_f32_16x16x32_bf16 v[66:69], v[184:187], v[224:227], v[66:69]
	v_mfma_f32_16x16x32_bf16 v[66:69], v[188:191], v[228:231], v[66:69]
	v_mfma_f32_16x16x32_bf16 v[70:73], v[162:165], v[224:227], v[70:73]
	v_mfma_f32_16x16x32_bf16 v[70:73], v[180:183], v[228:231], v[70:73]
	v_mfma_f32_16x16x32_bf16 v[74:77], v[138:141], v[224:227], v[74:77]
	v_mfma_f32_16x16x32_bf16 v[74:77], v[142:145], v[228:231], v[74:77]
	v_mfma_f32_16x16x32_bf16 v[78:81], v[130:133], v[224:227], v[78:81]
	v_mfma_f32_16x16x32_bf16 v[78:81], v[134:137], v[228:231], v[78:81]
	s_setprio 0
	s_waitcnt vmcnt(8)
	s_barrier
	ds_read_b128 v[196:199], v179 offset:16384
	ds_read_b128 v[200:203], v179 offset:17408
	ds_read_b128 v[204:207], v179 offset:18432
	ds_read_b128 v[208:211], v179 offset:19456
	ds_read_b128 v[212:215], v179 offset:20480
	ds_read_b128 v[220:223], v179 offset:21504
	ds_read_b128 v[224:227], v179 offset:22528
	ds_read_b128 v[228:231], v179 offset:23552
	s_add_u32 vcc_lo, s40, 0x100000
	s_addc_u32 vcc_hi, s41, 0
	s_add_i32 m0, s24, 0x10000
	s_nop 0
	global_load_lds_dwordx4 v148, s[40:41]
	s_add_i32 m0, s24, 0x12000
	s_nop 0
	global_load_lds_dwordx4 v152, s[40:41]
	s_add_i32 m0, s24, 0x14000
	s_nop 0
	global_load_lds_dwordx4 v148, vcc
	s_add_i32 m0, s24, 0x16000
	s_nop 0
	global_load_lds_dwordx4 v152, vcc
	s_mov_b32 m0, s24
	s_nop 0
	global_load_lds_dwordx4 v146, s[42:43]
	s_add_i32 m0, s24, 0x2000
	s_nop 0
	global_load_lds_dwordx4 v150, s[42:43]
	s_waitcnt lgkmcnt(0)
	s_setprio 1
	v_mfma_f32_16x16x32_bf16 v[62:65], v[130:133], v[196:199], v[62:65]
	v_mfma_f32_16x16x32_bf16 v[62:65], v[134:137], v[200:203], v[62:65]
	v_mfma_f32_16x16x32_bf16 v[58:61], v[138:141], v[196:199], v[58:61]
	v_mfma_f32_16x16x32_bf16 v[58:61], v[142:145], v[200:203], v[58:61]
	v_mfma_f32_16x16x32_bf16 v[54:57], v[162:165], v[196:199], v[54:57]
	v_mfma_f32_16x16x32_bf16 v[54:57], v[180:183], v[200:203], v[54:57]
	v_mfma_f32_16x16x32_bf16 v[50:53], v[184:187], v[196:199], v[50:53]
	v_mfma_f32_16x16x32_bf16 v[50:53], v[188:191], v[200:203], v[50:53]
	v_mfma_f32_16x16x32_bf16 v[34:37], v[184:187], v[204:207], v[34:37]
	v_mfma_f32_16x16x32_bf16 v[34:37], v[188:191], v[208:211], v[34:37]
	v_mfma_f32_16x16x32_bf16 v[38:41], v[162:165], v[204:207], v[38:41]
	v_mfma_f32_16x16x32_bf16 v[38:41], v[180:183], v[208:211], v[38:41]
	v_mfma_f32_16x16x32_bf16 v[42:45], v[138:141], v[204:207], v[42:45]
	v_mfma_f32_16x16x32_bf16 v[42:45], v[142:145], v[208:211], v[42:45]
	v_mfma_f32_16x16x32_bf16 v[46:49], v[130:133], v[204:207], v[46:49]
	v_mfma_f32_16x16x32_bf16 v[46:49], v[134:137], v[208:211], v[46:49]
	v_mfma_f32_16x16x32_bf16 v[30:33], v[130:133], v[212:215], v[30:33]
	v_mfma_f32_16x16x32_bf16 v[30:33], v[134:137], v[220:223], v[30:33]
	v_mfma_f32_16x16x32_bf16 v[26:29], v[138:141], v[212:215], v[26:29]
	v_mfma_f32_16x16x32_bf16 v[26:29], v[142:145], v[220:223], v[26:29]
	v_mfma_f32_16x16x32_bf16 v[22:25], v[162:165], v[212:215], v[22:25]
	v_mfma_f32_16x16x32_bf16 v[22:25], v[180:183], v[220:223], v[22:25]
	v_mfma_f32_16x16x32_bf16 v[18:21], v[184:187], v[212:215], v[18:21]
	v_mfma_f32_16x16x32_bf16 v[18:21], v[188:191], v[220:223], v[18:21]
	v_mfma_f32_16x16x32_bf16 v[2:5], v[184:187], v[224:227], v[2:5]
	v_mfma_f32_16x16x32_bf16 v[2:5], v[188:191], v[228:231], v[2:5]
	v_mfma_f32_16x16x32_bf16 v[6:9], v[162:165], v[224:227], v[6:9]
	v_mfma_f32_16x16x32_bf16 v[6:9], v[180:183], v[228:231], v[6:9]
	v_mfma_f32_16x16x32_bf16 v[10:13], v[138:141], v[224:227], v[10:13]
	v_mfma_f32_16x16x32_bf16 v[10:13], v[142:145], v[228:231], v[10:13]
	v_mfma_f32_16x16x32_bf16 v[14:17], v[130:133], v[224:227], v[14:17]
	v_mfma_f32_16x16x32_bf16 v[14:17], v[134:137], v[228:231], v[14:17]
	s_setprio 0
	s_waitcnt vmcnt(8)
	s_barrier
; #define PG8_STAGE(bufoff, gbase, voff) do { _Pragma("unroll") for (int _i = 0; _i < 2; ++_i) \
;         __builtin_amdgcn_global_load_lds((const unsigned*)((const char*)(gbase) + (voff)[_i]), (PG8_LAS unsigned*)(lds + (bufoff) + ldsw + _i * 8192), 16, 0, 0); } while (0)
; #define PG8_LDA(dst, b, h) do { _Pragma("unroll") for (int m = 0; m < 4; ++m) _Pragma("unroll") for (int k = 0; k < 2; ++k) dst[m][k] = *(const PG8_LAS bf16x8*)(lds + PG8_SA(b, h) + aoff + m * 2048 + k * 1024); } while (0)
; #define PG8_LDB(dst, b, h) do { _Pragma("unroll") for (int n = 0; n < 2; ++n) _Pragma("unroll") for (int k = 0; k < 2; ++k) dst[n][k] = *(const PG8_LAS bf16x8*)(lds + PG8_SB(b, h) + boff + n * 2048 + k * 1024); } while (0)
; #define PG8_MMA(ai, bj, At, Bt) do { __builtin_amdgcn_s_setprio(1); _Pragma("unroll") for (int m = 0; m < 4; ++m) _Pragma("unroll") for (int n = 0; n < 2; ++n) _Pragma("unroll") for (int k = 0; k < 2; ++k) \
;         acc[ai][bj][m][n] = __builtin_amdgcn_mfma_f32_16x16x32_bf16(Bt[n][k], At[m][k], acc[ai][bj][m][n], 0, 0, 0); __builtin_amdgcn_s_setprio(0); } while (0)
; #define PG8_WAIT_V(n) asm volatile("s_waitcnt vmcnt(" #n ")" ::: "memory")
; #define PG8_WAIT_L(n) asm volatile("s_waitcnt lgkmcnt(" #n ")" ::: "memory")
; #define PG8_BAR __builtin_amdgcn_s_barrier()
; #define PG8_SCHED __builtin_amdgcn_sched_barrier(0)
; template <class Epi, class Sched, bool ALIGN_EPI = false, bool SP2 = false>
; __device__ __forceinline__ void gemm_phase(PG8_LAS unsigned char* lds, const Gemm g, const Sched& S, const Epi& E) {
;     ...
;             PG8_LDB(B0, 1, 0); PG8_LDB(B1, 1, 1); PG8_SCHED; PG8_LDA(At, 1, 0); PG8_STAGE(PG8_SA(0, 1), a2 + hstep, voffA);
;             PG8_WAIT_V(8); PG8_WAIT_L(0); PG8_BAR; PG8_MMA(0, 0, At, B0); PG8_MMA(0, 1, At, B1); PG8_BAR; PG8_SCHED;
;             PG8_LDA(At, 1, 1); PG8_STAGE(PG8_SB(1, 0), b3, voffB); PG8_STAGE(PG8_SB(1, 1), b3 + hstep, voffB); PG8_STAGE(PG8_SA(1, 0), a3, voffA);
;             PG8_WAIT_V(8); PG8_WAIT_L(0); PG8_BAR; PG8_MMA(1, 0, At, B0); PG8_MMA(1, 1, At, B1); PG8_BAR; PG8_SCHED;
	s_add_i32 s59, 0, 0x18000
	s_add_i32 s60, 0, 0x1c000
	v_add_u32_e32 v142, s59, v166
	v_add_u32_e32 v188, s60, v166
	ds_read_b128 v[130:133], v142
	ds_read_b128 v[134:137], v142 offset:1024
	ds_read_b128 v[138:141], v142 offset:2048
	ds_read_b128 v[142:145], v142 offset:3072
	ds_read_b128 v[162:165], v188
	ds_read_b128 v[180:183], v188 offset:1024
	ds_read_b128 v[184:187], v188 offset:2048
	ds_read_b128 v[188:191], v188 offset:3072
	ds_read_b128 v[196:199], v179 offset:32768
	ds_read_b128 v[200:203], v179 offset:33792
	ds_read_b128 v[204:207], v179 offset:34816
	ds_read_b128 v[208:211], v179 offset:35840
	ds_read_b128 v[212:215], v179 offset:36864
	ds_read_b128 v[220:223], v179 offset:37888
	ds_read_b128 v[224:227], v179 offset:38912
	ds_read_b128 v[228:231], v179 offset:39936
	s_add_u32 vcc_lo, s42, 0x100000
	s_addc_u32 vcc_hi, s43, 0
	s_add_i32 m0, s24, 0x4000
	s_nop 0
	global_load_lds_dwordx4 v146, vcc
	s_add_i32 m0, s24, 0x6000
	s_nop 0
	global_load_lds_dwordx4 v150, vcc
	s_waitcnt lgkmcnt(0)
	s_setprio 1
	v_mfma_f32_16x16x32_bf16 v[126:129], v[130:133], v[196:199], v[126:129]
	v_mfma_f32_16x16x32_bf16 v[126:129], v[134:137], v[200:203], v[126:129]
	v_mfma_f32_16x16x32_bf16 v[122:125], v[138:141], v[196:199], v[122:125]
	v_mfma_f32_16x16x32_bf16 v[122:125], v[142:145], v[200:203], v[122:125]
	v_mfma_f32_16x16x32_bf16 v[118:121], v[162:165], v[196:199], v[118:121]
	v_mfma_f32_16x16x32_bf16 v[118:121], v[180:183], v[200:203], v[118:121]
	v_mfma_f32_16x16x32_bf16 v[114:117], v[184:187], v[196:199], v[114:117]
	v_mfma_f32_16x16x32_bf16 v[114:117], v[188:191], v[200:203], v[114:117]
	v_mfma_f32_16x16x32_bf16 v[98:101], v[184:187], v[204:207], v[98:101]
	v_mfma_f32_16x16x32_bf16 v[98:101], v[188:191], v[208:211], v[98:101]
	v_mfma_f32_16x16x32_bf16 v[102:105], v[162:165], v[204:207], v[102:105]
	v_mfma_f32_16x16x32_bf16 v[102:105], v[180:183], v[208:211], v[102:105]
	v_mfma_f32_16x16x32_bf16 v[106:109], v[138:141], v[204:207], v[106:109]
	v_mfma_f32_16x16x32_bf16 v[106:109], v[142:145], v[208:211], v[106:109]
	v_mfma_f32_16x16x32_bf16 v[110:113], v[130:133], v[204:207], v[110:113]
	v_mfma_f32_16x16x32_bf16 v[110:113], v[134:137], v[208:211], v[110:113]
	v_mfma_f32_16x16x32_bf16 v[94:97], v[130:133], v[212:215], v[94:97]
	v_mfma_f32_16x16x32_bf16 v[94:97], v[134:137], v[220:223], v[94:97]
	v_mfma_f32_16x16x32_bf16 v[90:93], v[138:141], v[212:215], v[90:93]
	v_mfma_f32_16x16x32_bf16 v[90:93], v[142:145], v[220:223], v[90:93]
	v_mfma_f32_16x16x32_bf16 v[86:89], v[162:165], v[212:215], v[86:89]
	v_mfma_f32_16x16x32_bf16 v[86:89], v[180:183], v[220:223], v[86:89]
	v_mfma_f32_16x16x32_bf16 v[82:85], v[184:187], v[212:215], v[82:85]
	v_mfma_f32_16x16x32_bf16 v[82:85], v[188:191], v[220:223], v[82:85]
	v_mfma_f32_16x16x32_bf16 v[66:69], v[184:187], v[224:227], v[66:69]
	v_mfma_f32_16x16x32_bf16 v[66:69], v[188:191], v[228:231], v[66:69]
	v_mfma_f32_16x16x32_bf16 v[70:73], v[162:165], v[224:227], v[70:73]
	v_mfma_f32_16x16x32_bf16 v[70:73], v[180:183], v[228:231], v[70:73]
	v_mfma_f32_16x16x32_bf16 v[74:77], v[138:141], v[224:227], v[74:77]
	v_mfma_f32_16x16x32_bf16 v[74:77], v[142:145], v[228:231], v[74:77]
	v_mfma_f32_16x16x32_bf16 v[78:81], v[130:133], v[224:227], v[78:81]
	v_mfma_f32_16x16x32_bf16 v[78:81], v[134:137], v[228:231], v[78:81]
	s_setprio 0
	s_waitcnt vmcnt(8)
	s_barrier
	ds_read_b128 v[196:199], v179 offset:49152
	ds_read_b128 v[200:203], v179 offset:50176
	ds_read_b128 v[204:207], v179 offset:51200
	ds_read_b128 v[208:211], v179 offset:52224
	ds_read_b128 v[212:215], v179 offset:53248
	ds_read_b128 v[220:223], v179 offset:54272
	ds_read_b128 v[224:227], v179 offset:55296
	ds_read_b128 v[228:231], v179 offset:56320
	s_add_u32 s60, s40, 0x80
	s_addc_u32 s61, s41, 0
	s_add_u32 vcc_lo, s60, 0x100000
	s_addc_u32 vcc_hi, s61, 0
	s_add_i32 m0, s24, 0x18000
	s_nop 0
	global_load_lds_dwordx4 v148, s[60:61]
	s_add_i32 m0, s24, 0x1a000
	s_nop 0
	global_load_lds_dwordx4 v152, s[60:61]
	s_add_i32 m0, s24, 0x1c000
	s_nop 0
	global_load_lds_dwordx4 v148, vcc
	s_add_i32 m0, s24, 0x1e000
	s_nop 0
	global_load_lds_dwordx4 v152, vcc
	s_add_u32 s60, s42, 0x80
	s_addc_u32 s61, s43, 0
	s_add_i32 m0, s24, 0x8000
	s_nop 0
	global_load_lds_dwordx4 v146, s[60:61]
	s_add_i32 m0, s24, 0xa000
	s_nop 0
	global_load_lds_dwordx4 v150, s[60:61]
	s_waitcnt lgkmcnt(0)
	s_setprio 1
	v_mfma_f32_16x16x32_bf16 v[62:65], v[130:133], v[196:199], v[62:65]
	v_mfma_f32_16x16x32_bf16 v[62:65], v[134:137], v[200:203], v[62:65]
	v_mfma_f32_16x16x32_bf16 v[58:61], v[138:141], v[196:199], v[58:61]
	v_mfma_f32_16x16x32_bf16 v[58:61], v[142:145], v[200:203], v[58:61]
	v_mfma_f32_16x16x32_bf16 v[54:57], v[162:165], v[196:199], v[54:57]
	v_mfma_f32_16x16x32_bf16 v[54:57], v[180:183], v[200:203], v[54:57]
	v_mfma_f32_16x16x32_bf16 v[50:53], v[184:187], v[196:199], v[50:53]
	v_mfma_f32_16x16x32_bf16 v[50:53], v[188:191], v[200:203], v[50:53]
	v_mfma_f32_16x16x32_bf16 v[34:37], v[184:187], v[204:207], v[34:37]
	v_mfma_f32_16x16x32_bf16 v[34:37], v[188:191], v[208:211], v[34:37]
	v_mfma_f32_16x16x32_bf16 v[38:41], v[162:165], v[204:207], v[38:41]
	v_mfma_f32_16x16x32_bf16 v[38:41], v[180:183], v[208:211], v[38:41]
	v_mfma_f32_16x16x32_bf16 v[42:45], v[138:141], v[204:207], v[42:45]
	v_mfma_f32_16x16x32_bf16 v[42:45], v[142:145], v[208:211], v[42:45]
	v_mfma_f32_16x16x32_bf16 v[46:49], v[130:133], v[204:207], v[46:49]
	v_mfma_f32_16x16x32_bf16 v[46:49], v[134:137], v[208:211], v[46:49]
	v_mfma_f32_16x16x32_bf16 v[30:33], v[130:133], v[212:215], v[30:33]
	v_mfma_f32_16x16x32_bf16 v[30:33], v[134:137], v[220:223], v[30:33]
	v_mfma_f32_16x16x32_bf16 v[26:29], v[138:141], v[212:215], v[26:29]
	v_mfma_f32_16x16x32_bf16 v[26:29], v[142:145], v[220:223], v[26:29]
	v_mfma_f32_16x16x32_bf16 v[22:25], v[162:165], v[212:215], v[22:25]
	v_mfma_f32_16x16x32_bf16 v[22:25], v[180:183], v[220:223], v[22:25]
	v_mfma_f32_16x16x32_bf16 v[18:21], v[184:187], v[212:215], v[18:21]
	v_mfma_f32_16x16x32_bf16 v[18:21], v[188:191], v[220:223], v[18:21]
	v_mfma_f32_16x16x32_bf16 v[2:5], v[184:187], v[224:227], v[2:5]
	v_mfma_f32_16x16x32_bf16 v[2:5], v[188:191], v[228:231], v[2:5]
	v_mfma_f32_16x16x32_bf16 v[6:9], v[162:165], v[224:227], v[6:9]
	v_mfma_f32_16x16x32_bf16 v[6:9], v[180:183], v[228:231], v[6:9]
	v_mfma_f32_16x16x32_bf16 v[10:13], v[138:141], v[224:227], v[10:13]
	v_mfma_f32_16x16x32_bf16 v[10:13], v[142:145], v[228:231], v[10:13]
	v_mfma_f32_16x16x32_bf16 v[14:17], v[130:133], v[224:227], v[14:17]
	v_mfma_f32_16x16x32_bf16 v[14:17], v[134:137], v[228:231], v[14:17]
	s_setprio 0
	s_waitcnt vmcnt(8)
	s_barrier
	s_add_i32 s58, s58, 2
	s_add_u32 s36, s36, 0x100
	s_addc_u32 s37, s37, 0
	s_add_u32 s56, s56, 0x100
	s_addc_u32 s57, s57, 0
	s_cmp_gt_u32 s58, 61
	s_cbranch_scc0 .LBB0_1251
	s_branch .Lf1_exit
; #define PG8_STAGE(bufoff, gbase, voff) do { _Pragma("unroll") for (int _i = 0; _i < 2; ++_i) \
;         __builtin_amdgcn_global_load_lds((const unsigned*)((const char*)(gbase) + (voff)[_i]), (PG8_LAS unsigned*)(lds + (bufoff) + ldsw + _i * 8192), 16, 0, 0); } while (0)
; #define PG8_LDA(dst, b, h) do { _Pragma("unroll") for (int m = 0; m < 4; ++m) _Pragma("unroll") for (int k = 0; k < 2; ++k) dst[m][k] = *(const PG8_LAS bf16x8*)(lds + PG8_SA(b, h) + aoff + m * 2048 + k * 1024); } while (0)
; #define PG8_LDB(dst, b, h) do { _Pragma("unroll") for (int n = 0; n < 2; ++n) _Pragma("unroll") for (int k = 0; k < 2; ++k) dst[n][k] = *(const PG8_LAS bf16x8*)(lds + PG8_SB(b, h) + boff + n * 2048 + k * 1024); } while (0)
; #define PG8_MMA(ai, bj, At, Bt) do { __builtin_amdgcn_s_setprio(1); _Pragma("unroll") for (int m = 0; m < 4; ++m) _Pragma("unroll") for (int n = 0; n < 2; ++n) _Pragma("unroll") for (int k = 0; k < 2; ++k) \
;         acc[ai][bj][m][n] = __builtin_amdgcn_mfma_f32_16x16x32_bf16(Bt[n][k], At[m][k], acc[ai][bj][m][n], 0, 0, 0); __builtin_amdgcn_s_setprio(0); } while (0)
; #define PG8_WAIT_V(n) asm volatile("s_waitcnt vmcnt(" #n ")" ::: "memory")
; #define PG8_WAIT_L(n) asm volatile("s_waitcnt lgkmcnt(" #n ")" ::: "memory")
; #define PG8_BAR __builtin_amdgcn_s_barrier()
; #define PG8_SCHED __builtin_amdgcn_sched_barrier(0)
; template <class Epi, class Sched, bool ALIGN_EPI = false, bool SP2 = false>
; __device__ __forceinline__ void gemm_phase(PG8_LAS unsigned char* lds, const Gemm g, const Sched& S, const Epi& E) {
;     ...
;             PG8_LDB(B0, 0, 0); PG8_LDB(B1, 0, 1); PG8_SCHED; PG8_LDA(At, 0, 0); PG8_STAGE(PG8_SA(1, 1), a1 + hstep, voffA);
;             PG8_WAIT_V(8); PG8_WAIT_L(0); PG8_BAR; PG8_MMA(0, 0, At, B0); PG8_MMA(0, 1, At, B1); PG8_BAR; PG8_SCHED;
;             PG8_LDA(At, 0, 1); PG8_STAGE(PG8_SB(0, 0), b2, voffB); PG8_STAGE(PG8_SB(0, 1), b2 + hstep, voffB); PG8_STAGE(PG8_SA(0, 0), a2, voffA);
;             PG8_WAIT_V(8); PG8_WAIT_L(0); PG8_BAR; PG8_MMA(1, 0, At, B0); PG8_MMA(1, 1, At, B1); PG8_BAR; PG8_SCHED;
.Lf1_h1:
	ds_read_b128 v[130:133], v177
	ds_read_b128 v[134:137], v177 offset:1024
	ds_read_b128 v[138:141], v177 offset:2048
	ds_read_b128 v[142:145], v177 offset:3072
	ds_read_b128 v[162:165], v178
	ds_read_b128 v[180:183], v178 offset:1024
	ds_read_b128 v[184:187], v178 offset:2048
	ds_read_b128 v[188:191], v178 offset:3072
	s_add_u32 s40, s36, 0xfff00080
	s_addc_u32 s41, s37, -1
	s_cmp_eq_u32 s58, 60
	s_cselect_b32 s43, s15, s41
	s_cselect_b32 s42, s17, s40
	s_cselect_b32 s41, s54, s57
	s_cselect_b32 s40, s55, s56
	ds_read_b128 v[196:199], v179
	ds_read_b128 v[200:203], v179 offset:1024
	ds_read_b128 v[204:207], v179 offset:2048
	ds_read_b128 v[208:211], v179 offset:3072
	ds_read_b128 v[212:215], v179 offset:4096
	ds_read_b128 v[220:223], v179 offset:5120
	ds_read_b128 v[224:227], v179 offset:6144
	ds_read_b128 v[228:231], v179 offset:7168
	s_add_i32 m0, s24, 0xc000
	s_nop 0
	global_load_lds_dwordx4 v146, s[36:37]
	s_add_i32 m0, s24, 0xe000
	s_nop 0
	global_load_lds_dwordx4 v150, s[36:37]
	s_sleep 2
	s_waitcnt lgkmcnt(0)
	s_waitcnt vmcnt(8)
	s_barrier
	s_setprio 2
	v_mfma_f32_16x16x32_bf16 v[126:129], v[130:133], v[196:199], v[126:129]
	v_mfma_f32_16x16x32_bf16 v[126:129], v[134:137], v[200:203], v[126:129]
	v_mfma_f32_16x16x32_bf16 v[122:125], v[138:141], v[196:199], v[122:125]
	v_mfma_f32_16x16x32_bf16 v[122:125], v[142:145], v[200:203], v[122:125]
	v_mfma_f32_16x16x32_bf16 v[118:121], v[162:165], v[196:199], v[118:121]
	v_mfma_f32_16x16x32_bf16 v[118:121], v[180:183], v[200:203], v[118:121]
	v_mfma_f32_16x16x32_bf16 v[114:117], v[184:187], v[196:199], v[114:117]
	v_mfma_f32_16x16x32_bf16 v[114:117], v[188:191], v[200:203], v[114:117]
	v_mfma_f32_16x16x32_bf16 v[98:101], v[184:187], v[204:207], v[98:101]
	v_mfma_f32_16x16x32_bf16 v[98:101], v[188:191], v[208:211], v[98:101]
	v_mfma_f32_16x16x32_bf16 v[102:105], v[162:165], v[204:207], v[102:105]
	v_mfma_f32_16x16x32_bf16 v[102:105], v[180:183], v[208:211], v[102:105]
	v_mfma_f32_16x16x32_bf16 v[106:109], v[138:141], v[204:207], v[106:109]
	v_mfma_f32_16x16x32_bf16 v[106:109], v[142:145], v[208:211], v[106:109]
	v_mfma_f32_16x16x32_bf16 v[110:113], v[130:133], v[204:207], v[110:113]
	v_mfma_f32_16x16x32_bf16 v[110:113], v[134:137], v[208:211], v[110:113]
	v_mfma_f32_16x16x32_bf16 v[94:97], v[130:133], v[212:215], v[94:97]
	v_mfma_f32_16x16x32_bf16 v[94:97], v[134:137], v[220:223], v[94:97]
	v_mfma_f32_16x16x32_bf16 v[90:93], v[138:141], v[212:215], v[90:93]
	v_mfma_f32_16x16x32_bf16 v[90:93], v[142:145], v[220:223], v[90:93]
	v_mfma_f32_16x16x32_bf16 v[86:89], v[162:165], v[212:215], v[86:89]
	v_mfma_f32_16x16x32_bf16 v[86:89], v[180:183], v[220:223], v[86:89]
	v_mfma_f32_16x16x32_bf16 v[82:85], v[184:187], v[212:215], v[82:85]
	v_mfma_f32_16x16x32_bf16 v[82:85], v[188:191], v[220:223], v[82:85]
	v_mfma_f32_16x16x32_bf16 v[66:69], v[184:187], v[224:227], v[66:69]
	v_mfma_f32_16x16x32_bf16 v[66:69], v[188:191], v[228:231], v[66:69]
	v_mfma_f32_16x16x32_bf16 v[70:73], v[162:165], v[224:227], v[70:73]
	v_mfma_f32_16x16x32_bf16 v[70:73], v[180:183], v[228:231], v[70:73]
	v_mfma_f32_16x16x32_bf16 v[74:77], v[138:141], v[224:227], v[74:77]
	v_mfma_f32_16x16x32_bf16 v[74:77], v[142:145], v[228:231], v[74:77]
	v_mfma_f32_16x16x32_bf16 v[78:81], v[130:133], v[224:227], v[78:81]
	v_mfma_f32_16x16x32_bf16 v[78:81], v[134:137], v[228:231], v[78:81]
	s_setprio 0
	ds_read_b128 v[196:199], v179 offset:16384
	ds_read_b128 v[200:203], v179 offset:17408
	ds_read_b128 v[204:207], v179 offset:18432
	ds_read_b128 v[208:211], v179 offset:19456
	ds_read_b128 v[212:215], v179 offset:20480
	ds_read_b128 v[220:223], v179 offset:21504
	ds_read_b128 v[224:227], v179 offset:22528
	ds_read_b128 v[228:231], v179 offset:23552
	s_add_u32 vcc_lo, s40, 0x100000
	s_addc_u32 vcc_hi, s41, 0
	s_add_i32 m0, s24, 0x10000
	s_nop 0
	global_load_lds_dwordx4 v148, s[40:41]
	s_add_i32 m0, s24, 0x12000
	s_nop 0
	global_load_lds_dwordx4 v152, s[40:41]
	s_add_i32 m0, s24, 0x14000
	s_nop 0
	global_load_lds_dwordx4 v148, vcc
	s_add_i32 m0, s24, 0x16000
	s_nop 0
	global_load_lds_dwordx4 v152, vcc
	s_mov_b32 m0, s24
	s_nop 0
	global_load_lds_dwordx4 v146, s[42:43]
	s_add_i32 m0, s24, 0x2000
	s_nop 0
	global_load_lds_dwordx4 v150, s[42:43]
	s_sleep 2
	s_waitcnt lgkmcnt(0)
	s_waitcnt vmcnt(8)
	s_barrier
; #define PG8_STAGE(bufoff, gbase, voff) do { _Pragma("unroll") for (int _i = 0; _i < 2; ++_i) \
;         __builtin_amdgcn_global_load_lds((const unsigned*)((const char*)(gbase) + (voff)[_i]), (PG8_LAS unsigned*)(lds + (bufoff) + ldsw + _i * 8192), 16, 0, 0); } while (0)
; #define PG8_LDA(dst, b, h) do { _Pragma("unroll") for (int m = 0; m < 4; ++m) _Pragma("unroll") for (int k = 0; k < 2; ++k) dst[m][k] = *(const PG8_LAS bf16x8*)(lds + PG8_SA(b, h) + aoff + m * 2048 + k * 1024); } while (0)
; #define PG8_LDB(dst, b, h) do { _Pragma("unroll") for (int n = 0; n < 2; ++n) _Pragma("unroll") for (int k = 0; k < 2; ++k) dst[n][k] = *(const PG8_LAS bf16x8*)(lds + PG8_SB(b, h) + boff + n * 2048 + k * 1024); } while (0)
; #define PG8_MMA(ai, bj, At, Bt) do { __builtin_amdgcn_s_setprio(1); _Pragma("unroll") for (int m = 0; m < 4; ++m) _Pragma("unroll") for (int n = 0; n < 2; ++n) _Pragma("unroll") for (int k = 0; k < 2; ++k) \
;         acc[ai][bj][m][n] = __builtin_amdgcn_mfma_f32_16x16x32_bf16(Bt[n][k], At[m][k], acc[ai][bj][m][n], 0, 0, 0); __builtin_amdgcn_s_setprio(0); } while (0)
; #define PG8_WAIT_V(n) asm volatile("s_waitcnt vmcnt(" #n ")" ::: "memory")
; #define PG8_WAIT_L(n) asm volatile("s_waitcnt lgkmcnt(" #n ")" ::: "memory")
; #define PG8_BAR __builtin_amdgcn_s_barrier()
; #define PG8_SCHED __builtin_amdgcn_sched_barrier(0)
; template <class Epi, class Sched, bool ALIGN_EPI = false, bool SP2 = false>
; __device__ __forceinline__ void gemm_phase(PG8_LAS unsigned char* lds, const Gemm g, const Sched& S, const Epi& E) {
;     ...
;             PG8_WAIT_V(8); PG8_WAIT_L(0); PG8_BAR; PG8_MMA(1, 0, At, B0); PG8_MMA(1, 1, At, B1); PG8_BAR; PG8_SCHED;
;             PG8_LDB(B0, 1, 0); PG8_LDB(B1, 1, 1); PG8_SCHED; PG8_LDA(At, 1, 0); PG8_STAGE(PG8_SA(0, 1), a2 + hstep, voffA);
;             PG8_WAIT_V(8); PG8_WAIT_L(0); PG8_BAR; PG8_MMA(0, 0, At, B0); PG8_MMA(0, 1, At, B1); PG8_BAR; PG8_SCHED;
	s_setprio 2
	v_mfma_f32_16x16x32_bf16 v[62:65], v[130:133], v[196:199], v[62:65]
	v_mfma_f32_16x16x32_bf16 v[62:65], v[134:137], v[200:203], v[62:65]
	v_mfma_f32_16x16x32_bf16 v[58:61], v[138:141], v[196:199], v[58:61]
	v_mfma_f32_16x16x32_bf16 v[58:61], v[142:145], v[200:203], v[58:61]
	v_mfma_f32_16x16x32_bf16 v[54:57], v[162:165], v[196:199], v[54:57]
	v_mfma_f32_16x16x32_bf16 v[54:57], v[180:183], v[200:203], v[54:57]
	v_mfma_f32_16x16x32_bf16 v[50:53], v[184:187], v[196:199], v[50:53]
	v_mfma_f32_16x16x32_bf16 v[50:53], v[188:191], v[200:203], v[50:53]
	v_mfma_f32_16x16x32_bf16 v[34:37], v[184:187], v[204:207], v[34:37]
	v_mfma_f32_16x16x32_bf16 v[34:37], v[188:191], v[208:211], v[34:37]
	v_mfma_f32_16x16x32_bf16 v[38:41], v[162:165], v[204:207], v[38:41]
	v_mfma_f32_16x16x32_bf16 v[38:41], v[180:183], v[208:211], v[38:41]
	v_mfma_f32_16x16x32_bf16 v[42:45], v[138:141], v[204:207], v[42:45]
	v_mfma_f32_16x16x32_bf16 v[42:45], v[142:145], v[208:211], v[42:45]
	v_mfma_f32_16x16x32_bf16 v[46:49], v[130:133], v[204:207], v[46:49]
	v_mfma_f32_16x16x32_bf16 v[46:49], v[134:137], v[208:211], v[46:49]
	v_mfma_f32_16x16x32_bf16 v[30:33], v[130:133], v[212:215], v[30:33]
	v_mfma_f32_16x16x32_bf16 v[30:33], v[134:137], v[220:223], v[30:33]
	v_mfma_f32_16x16x32_bf16 v[26:29], v[138:141], v[212:215], v[26:29]
	v_mfma_f32_16x16x32_bf16 v[26:29], v[142:145], v[220:223], v[26:29]
	v_mfma_f32_16x16x32_bf16 v[22:25], v[162:165], v[212:215], v[22:25]
	v_mfma_f32_16x16x32_bf16 v[22:25], v[180:183], v[220:223], v[22:25]
	v_mfma_f32_16x16x32_bf16 v[18:21], v[184:187], v[212:215], v[18:21]
	v_mfma_f32_16x16x32_bf16 v[18:21], v[188:191], v[220:223], v[18:21]
	v_mfma_f32_16x16x32_bf16 v[2:5], v[184:187], v[224:227], v[2:5]
	v_mfma_f32_16x16x32_bf16 v[2:5], v[188:191], v[228:231], v[2:5]
	v_mfma_f32_16x16x32_bf16 v[6:9], v[162:165], v[224:227], v[6:9]
	v_mfma_f32_16x16x32_bf16 v[6:9], v[180:183], v[228:231], v[6:9]
	v_mfma_f32_16x16x32_bf16 v[10:13], v[138:141], v[224:227], v[10:13]
	v_mfma_f32_16x16x32_bf16 v[10:13], v[142:145], v[228:231], v[10:13]
	v_mfma_f32_16x16x32_bf16 v[14:17], v[130:133], v[224:227], v[14:17]
	v_mfma_f32_16x16x32_bf16 v[14:17], v[134:137], v[228:231], v[14:17]
	s_setprio 0
	s_add_i32 s59, 0, 0x18000
	s_add_i32 s60, 0, 0x1c000
	v_add_u32_e32 v142, s59, v166
	v_add_u32_e32 v188, s60, v166
	ds_read_b128 v[130:133], v142
	ds_read_b128 v[134:137], v142 offset:1024
	ds_read_b128 v[138:141], v142 offset:2048
	ds_read_b128 v[142:145], v142 offset:3072
	ds_read_b128 v[162:165], v188
	ds_read_b128 v[180:183], v188 offset:1024
	ds_read_b128 v[184:187], v188 offset:2048
	ds_read_b128 v[188:191], v188 offset:3072
	ds_read_b128 v[196:199], v179 offset:32768
	ds_read_b128 v[200:203], v179 offset:33792
	ds_read_b128 v[204:207], v179 offset:34816
	ds_read_b128 v[208:211], v179 offset:35840
	ds_read_b128 v[212:215], v179 offset:36864
	ds_read_b128 v[220:223], v179 offset:37888
	ds_read_b128 v[224:227], v179 offset:38912
	ds_read_b128 v[228:231], v179 offset:39936
	s_add_u32 vcc_lo, s42, 0x100000
	s_addc_u32 vcc_hi, s43, 0
	s_add_i32 m0, s24, 0x4000
	s_nop 0
	global_load_lds_dwordx4 v146, vcc
	s_add_i32 m0, s24, 0x6000
	s_nop 0
	global_load_lds_dwordx4 v150, vcc
	s_sleep 2
	s_waitcnt lgkmcnt(0)
	s_waitcnt vmcnt(8)
	s_barrier
; #define PG8_STAGE(bufoff, gbase, voff) do { _Pragma("unroll") for (int _i = 0; _i < 2; ++_i) \
;         __builtin_amdgcn_global_load_lds((const unsigned*)((const char*)(gbase) + (voff)[_i]), (PG8_LAS unsigned*)(lds + (bufoff) + ldsw + _i * 8192), 16, 0, 0); } while (0)
; #define PG8_LDA(dst, b, h) do { _Pragma("unroll") for (int m = 0; m < 4; ++m) _Pragma("unroll") for (int k = 0; k < 2; ++k) dst[m][k] = *(const PG8_LAS bf16x8*)(lds + PG8_SA(b, h) + aoff + m * 2048 + k * 1024); } while (0)
; #define PG8_MMA(ai, bj, At, Bt) do { __builtin_amdgcn_s_setprio(1); _Pragma("unroll") for (int m = 0; m < 4; ++m) _Pragma("unroll") for (int n = 0; n < 2; ++n) _Pragma("unroll") for (int k = 0; k < 2; ++k) \
;         acc[ai][bj][m][n] = __builtin_amdgcn_mfma_f32_16x16x32_bf16(Bt[n][k], At[m][k], acc[ai][bj][m][n], 0, 0, 0); __builtin_amdgcn_s_setprio(0); } while (0)
; #define PG8_WAIT_V(n) asm volatile("s_waitcnt vmcnt(" #n ")" ::: "memory")
; #define PG8_WAIT_L(n) asm volatile("s_waitcnt lgkmcnt(" #n ")" ::: "memory")
; #define PG8_BAR __builtin_amdgcn_s_barrier()
; #define PG8_SCHED __builtin_amdgcn_sched_barrier(0)
; template <class Epi, class Sched, bool ALIGN_EPI = false, bool SP2 = false>
; __device__ __forceinline__ void gemm_phase(PG8_LAS unsigned char* lds, const Gemm g, const Sched& S, const Epi& E) {
;     ...
;             PG8_WAIT_V(8); PG8_WAIT_L(0); PG8_BAR; PG8_MMA(0, 0, At, B0); PG8_MMA(0, 1, At, B1); PG8_BAR; PG8_SCHED;
;             PG8_LDA(At, 1, 1); PG8_STAGE(PG8_SB(1, 0), b3, voffB); PG8_STAGE(PG8_SB(1, 1), b3 + hstep, voffB); PG8_STAGE(PG8_SA(1, 0), a3, voffA);
;             PG8_WAIT_V(8); PG8_WAIT_L(0); PG8_BAR; PG8_MMA(1, 0, At, B0); PG8_MMA(1, 1, At, B1); PG8_BAR; PG8_SCHED;
	s_setprio 2
	v_mfma_f32_16x16x32_bf16 v[126:129], v[130:133], v[196:199], v[126:129]
	v_mfma_f32_16x16x32_bf16 v[126:129], v[134:137], v[200:203], v[126:129]
	v_mfma_f32_16x16x32_bf16 v[122:125], v[138:141], v[196:199], v[122:125]
	v_mfma_f32_16x16x32_bf16 v[122:125], v[142:145], v[200:203], v[122:125]
	v_mfma_f32_16x16x32_bf16 v[118:121], v[162:165], v[196:199], v[118:121]
	v_mfma_f32_16x16x32_bf16 v[118:121], v[180:183], v[200:203], v[118:121]
	v_mfma_f32_16x16x32_bf16 v[114:117], v[184:187], v[196:199], v[114:117]
	v_mfma_f32_16x16x32_bf16 v[114:117], v[188:191], v[200:203], v[114:117]
	v_mfma_f32_16x16x32_bf16 v[98:101], v[184:187], v[204:207], v[98:101]
	v_mfma_f32_16x16x32_bf16 v[98:101], v[188:191], v[208:211], v[98:101]
	v_mfma_f32_16x16x32_bf16 v[102:105], v[162:165], v[204:207], v[102:105]
	v_mfma_f32_16x16x32_bf16 v[102:105], v[180:183], v[208:211], v[102:105]
	v_mfma_f32_16x16x32_bf16 v[106:109], v[138:141], v[204:207], v[106:109]
	v_mfma_f32_16x16x32_bf16 v[106:109], v[142:145], v[208:211], v[106:109]
	v_mfma_f32_16x16x32_bf16 v[110:113], v[130:133], v[204:207], v[110:113]
	v_mfma_f32_16x16x32_bf16 v[110:113], v[134:137], v[208:211], v[110:113]
	v_mfma_f32_16x16x32_bf16 v[94:97], v[130:133], v[212:215], v[94:97]
	v_mfma_f32_16x16x32_bf16 v[94:97], v[134:137], v[220:223], v[94:97]
	v_mfma_f32_16x16x32_bf16 v[90:93], v[138:141], v[212:215], v[90:93]
	v_mfma_f32_16x16x32_bf16 v[90:93], v[142:145], v[220:223], v[90:93]
	v_mfma_f32_16x16x32_bf16 v[86:89], v[162:165], v[212:215], v[86:89]
	v_mfma_f32_16x16x32_bf16 v[86:89], v[180:183], v[220:223], v[86:89]
	v_mfma_f32_16x16x32_bf16 v[82:85], v[184:187], v[212:215], v[82:85]
	v_mfma_f32_16x16x32_bf16 v[82:85], v[188:191], v[220:223], v[82:85]
	v_mfma_f32_16x16x32_bf16 v[66:69], v[184:187], v[224:227], v[66:69]
	v_mfma_f32_16x16x32_bf16 v[66:69], v[188:191], v[228:231], v[66:69]
	v_mfma_f32_16x16x32_bf16 v[70:73], v[162:165], v[224:227], v[70:73]
	v_mfma_f32_16x16x32_bf16 v[70:73], v[180:183], v[228:231], v[70:73]
	v_mfma_f32_16x16x32_bf16 v[74:77], v[138:141], v[224:227], v[74:77]
	v_mfma_f32_16x16x32_bf16 v[74:77], v[142:145], v[228:231], v[74:77]
	v_mfma_f32_16x16x32_bf16 v[78:81], v[130:133], v[224:227], v[78:81]
	v_mfma_f32_16x16x32_bf16 v[78:81], v[134:137], v[228:231], v[78:81]
	s_setprio 0
	ds_read_b128 v[196:199], v179 offset:49152
	ds_read_b128 v[200:203], v179 offset:50176
	ds_read_b128 v[204:207], v179 offset:51200
	ds_read_b128 v[208:211], v179 offset:52224
	ds_read_b128 v[212:215], v179 offset:53248
	ds_read_b128 v[220:223], v179 offset:54272
	ds_read_b128 v[224:227], v179 offset:55296
	ds_read_b128 v[228:231], v179 offset:56320
	s_add_u32 s60, s40, 0x80
	s_addc_u32 s61, s41, 0
	s_add_u32 vcc_lo, s60, 0x100000
	s_addc_u32 vcc_hi, s61, 0
	s_add_i32 m0, s24, 0x18000
	s_nop 0
	global_load_lds_dwordx4 v148, s[60:61]
	s_add_i32 m0, s24, 0x1a000
	s_nop 0
	global_load_lds_dwordx4 v152, s[60:61]
	s_add_i32 m0, s24, 0x1c000
	s_nop 0
	global_load_lds_dwordx4 v148, vcc
	s_add_i32 m0, s24, 0x1e000
	s_nop 0
	global_load_lds_dwordx4 v152, vcc
	s_add_u32 s60, s42, 0x80
	s_addc_u32 s61, s43, 0
	s_add_i32 m0, s24, 0x8000
	s_nop 0
	global_load_lds_dwordx4 v146, s[60:61]
	s_add_i32 m0, s24, 0xa000
	s_nop 0
	global_load_lds_dwordx4 v150, s[60:61]
	s_sleep 2
	s_waitcnt lgkmcnt(0)
	s_waitcnt vmcnt(8)
	s_barrier
	s_setprio 2
	v_mfma_f32_16x16x32_bf16 v[62:65], v[130:133], v[196:199], v[62:65]
	v_mfma_f32_16x16x32_bf16 v[62:65], v[134:137], v[200:203], v[62:65]
	v_mfma_f32_16x16x32_bf16 v[58:61], v[138:141], v[196:199], v[58:61]
	v_mfma_f32_16x16x32_bf16 v[58:61], v[142:145], v[200:203], v[58:61]
	v_mfma_f32_16x16x32_bf16 v[54:57], v[162:165], v[196:199], v[54:57]
	v_mfma_f32_16x16x32_bf16 v[54:57], v[180:183], v[200:203], v[54:57]
	v_mfma_f32_16x16x32_bf16 v[50:53], v[184:187], v[196:199], v[50:53]
	v_mfma_f32_16x16x32_bf16 v[50:53], v[188:191], v[200:203], v[50:53]
	v_mfma_f32_16x16x32_bf16 v[34:37], v[184:187], v[204:207], v[34:37]
	v_mfma_f32_16x16x32_bf16 v[34:37], v[188:191], v[208:211], v[34:37]
	v_mfma_f32_16x16x32_bf16 v[38:41], v[162:165], v[204:207], v[38:41]
	v_mfma_f32_16x16x32_bf16 v[38:41], v[180:183], v[208:211], v[38:41]
	v_mfma_f32_16x16x32_bf16 v[42:45], v[138:141], v[204:207], v[42:45]
	v_mfma_f32_16x16x32_bf16 v[42:45], v[142:145], v[208:211], v[42:45]
	v_mfma_f32_16x16x32_bf16 v[46:49], v[130:133], v[204:207], v[46:49]
	v_mfma_f32_16x16x32_bf16 v[46:49], v[134:137], v[208:211], v[46:49]
	v_mfma_f32_16x16x32_bf16 v[30:33], v[130:133], v[212:215], v[30:33]
	v_mfma_f32_16x16x32_bf16 v[30:33], v[134:137], v[220:223], v[30:33]
	v_mfma_f32_16x16x32_bf16 v[26:29], v[138:141], v[212:215], v[26:29]
	v_mfma_f32_16x16x32_bf16 v[26:29], v[142:145], v[220:223], v[26:29]
	v_mfma_f32_16x16x32_bf16 v[22:25], v[162:165], v[212:215], v[22:25]
	v_mfma_f32_16x16x32_bf16 v[22:25], v[180:183], v[220:223], v[22:25]
	v_mfma_f32_16x16x32_bf16 v[18:21], v[184:187], v[212:215], v[18:21]
	v_mfma_f32_16x16x32_bf16 v[18:21], v[188:191], v[220:223], v[18:21]
	v_mfma_f32_16x16x32_bf16 v[2:5], v[184:187], v[224:227], v[2:5]
	v_mfma_f32_16x16x32_bf16 v[2:5], v[188:191], v[228:231], v[2:5]
	v_mfma_f32_16x16x32_bf16 v[6:9], v[162:165], v[224:227], v[6:9]
	v_mfma_f32_16x16x32_bf16 v[6:9], v[180:183], v[228:231], v[6:9]
	v_mfma_f32_16x16x32_bf16 v[10:13], v[138:141], v[224:227], v[10:13]
	v_mfma_f32_16x16x32_bf16 v[10:13], v[142:145], v[228:231], v[10:13]
	v_mfma_f32_16x16x32_bf16 v[14:17], v[130:133], v[224:227], v[14:17]
	v_mfma_f32_16x16x32_bf16 v[14:17], v[134:137], v[228:231], v[14:17]
	s_setprio 0
	s_add_i32 s58, s58, 2
	s_add_u32 s36, s36, 0x100
	s_addc_u32 s37, s37, 0
	s_add_u32 s56, s56, 0x100
	s_addc_u32 s57, s57, 0
	s_cmp_gt_u32 s58, 61
	s_cbranch_scc0 .Lf1_h1

; #define PG8_STAGE(bufoff, gbase, voff) do { _Pragma("unroll") for (int _i = 0; _i < 2; ++_i) \
;         __builtin_amdgcn_global_load_lds((const unsigned*)((const char*)(gbase) + (voff)[_i]), (PG8_LAS unsigned*)(lds + (bufoff) + ldsw + _i * 8192), 16, 0, 0); } while (0)
; #define PG8_LDA(dst, b, h) do { _Pragma("unroll") for (int m = 0; m < 4; ++m) _Pragma("unroll") for (int k = 0; k < 2; ++k) dst[m][k] = *(const PG8_LAS bf16x8*)(lds + PG8_SA(b, h) + aoff + m * 2048 + k * 1024); } while (0)
; #define PG8_LDB(dst, b, h) do { _Pragma("unroll") for (int n = 0; n < 2; ++n) _Pragma("unroll") for (int k = 0; k < 2; ++k) dst[n][k] = *(const PG8_LAS bf16x8*)(lds + PG8_SB(b, h) + boff + n * 2048 + k * 1024); } while (0)
; #define PG8_MMA(ai, bj, At, Bt) do { __builtin_amdgcn_s_setprio(1); _Pragma("unroll") for (int m = 0; m < 4; ++m) _Pragma("unroll") for (int n = 0; n < 2; ++n) _Pragma("unroll") for (int k = 0; k < 2; ++k) \
;         acc[ai][bj][m][n] = __builtin_amdgcn_mfma_f32_16x16x32_bf16(Bt[n][k], At[m][k], acc[ai][bj][m][n], 0, 0, 0); __builtin_amdgcn_s_setprio(0); } while (0)
; #define PG8_WAIT_V(n) asm volatile("s_waitcnt vmcnt(" #n ")" ::: "memory")
; #define PG8_WAIT_L(n) asm volatile("s_waitcnt lgkmcnt(" #n ")" ::: "memory")
; #define PG8_BAR __builtin_amdgcn_s_barrier()
; #define PG8_SCHED __builtin_amdgcn_sched_barrier(0)
; template <class Epi, class Sched, bool ALIGN_EPI = false, bool SP2 = false>
; __device__ __forceinline__ void gemm_phase(PG8_LAS unsigned char* lds, const Gemm g, const Sched& S, const Epi& E) {
;     ...
;             PG8_LDB(B0, 0, 0); PG8_LDB(B1, 0, 1); PG8_SCHED; PG8_LDA(At, 0, 0); PG8_STAGE(PG8_SA(1, 1), a1 + hstep, voffA);
;             PG8_WAIT_V(8); PG8_WAIT_L(0); PG8_BAR; PG8_MMA(0, 0, At, B0); PG8_MMA(0, 1, At, B1); PG8_BAR; PG8_SCHED;
;             PG8_LDA(At, 0, 1); PG8_STAGE(PG8_SB(0, 0), b2, voffB); PG8_STAGE(PG8_SB(0, 1), b2 + hstep, voffB); PG8_STAGE(PG8_SA(0, 0), a2, voffA);
;             PG8_WAIT_V(8); PG8_WAIT_L(0); PG8_BAR; PG8_MMA(1, 0, At, B0); PG8_MMA(1, 1, At, B1); PG8_BAR; PG8_SCHED;
.LBB0_1321:
	ds_read_b128 v[128:131], v156
	ds_read_b128 v[132:135], v156 offset:1024
	ds_read_b128 v[150:153], v156 offset:2048
	ds_read_b128 v[162:165], v156 offset:3072
	ds_read_b128 v[166:169], v157
	ds_read_b128 v[170:173], v157 offset:1024
	ds_read_b128 v[174:177], v157 offset:2048
	ds_read_b128 v[178:181], v157 offset:3072
	s_add_u32 s20, s18, 0xffbfc080
	s_addc_u32 s21, s19, -1
	s_cmpk_eq_i32 s59, 0xfc
	s_cselect_b32 s23, s7, s21
	s_cselect_b32 s22, s6, s20
	s_cselect_b32 s21, s17, s58
	s_cselect_b32 s20, s16, s57
	ds_read_b128 v[182:185], v158
	ds_read_b128 v[186:189], v158 offset:1024
	ds_read_b128 v[190:193], v158 offset:2048
	ds_read_b128 v[194:197], v158 offset:3072
	ds_read_b128 v[198:201], v158 offset:4096
	ds_read_b128 v[202:205], v158 offset:5120
	ds_read_b128 v[206:209], v158 offset:6144
	ds_read_b128 v[210:213], v158 offset:7168
	s_add_i32 m0, s24, 0xc000
	s_nop 0
	global_load_lds_dwordx4 v136, s[18:19]
	s_add_i32 m0, s24, 0xe000
	s_nop 0
	global_load_lds_dwordx4 v140, s[18:19]
	s_waitcnt lgkmcnt(0)
	s_setprio 1
	v_mfma_f32_16x16x32_bf16 v[124:127], v[128:131], v[182:185], v[124:127]
	v_mfma_f32_16x16x32_bf16 v[124:127], v[132:135], v[186:189], v[124:127]
	v_mfma_f32_16x16x32_bf16 v[120:123], v[150:153], v[182:185], v[120:123]
	v_mfma_f32_16x16x32_bf16 v[120:123], v[162:165], v[186:189], v[120:123]
	v_mfma_f32_16x16x32_bf16 v[68:71], v[166:169], v[182:185], v[68:71]
	v_mfma_f32_16x16x32_bf16 v[68:71], v[170:173], v[186:189], v[68:71]
	v_mfma_f32_16x16x32_bf16 v[64:67], v[174:177], v[182:185], v[64:67]
	v_mfma_f32_16x16x32_bf16 v[64:67], v[178:181], v[186:189], v[64:67]
	v_mfma_f32_16x16x32_bf16 v[48:51], v[174:177], v[190:193], v[48:51]
	v_mfma_f32_16x16x32_bf16 v[48:51], v[178:181], v[194:197], v[48:51]
	v_mfma_f32_16x16x32_bf16 v[52:55], v[166:169], v[190:193], v[52:55]
	v_mfma_f32_16x16x32_bf16 v[52:55], v[170:173], v[194:197], v[52:55]
	v_mfma_f32_16x16x32_bf16 v[112:115], v[150:153], v[190:193], v[112:115]
	v_mfma_f32_16x16x32_bf16 v[112:115], v[162:165], v[194:197], v[112:115]
	v_mfma_f32_16x16x32_bf16 v[116:119], v[128:131], v[190:193], v[116:119]
	v_mfma_f32_16x16x32_bf16 v[116:119], v[132:135], v[194:197], v[116:119]
	v_mfma_f32_16x16x32_bf16 v[108:111], v[128:131], v[198:201], v[108:111]
	v_mfma_f32_16x16x32_bf16 v[108:111], v[132:135], v[202:205], v[108:111]
	v_mfma_f32_16x16x32_bf16 v[104:107], v[150:153], v[198:201], v[104:107]
	v_mfma_f32_16x16x32_bf16 v[104:107], v[162:165], v[202:205], v[104:107]
	v_mfma_f32_16x16x32_bf16 v[44:47], v[166:169], v[198:201], v[44:47]
	v_mfma_f32_16x16x32_bf16 v[44:47], v[170:173], v[202:205], v[44:47]
	v_mfma_f32_16x16x32_bf16 v[40:43], v[174:177], v[198:201], v[40:43]
	v_mfma_f32_16x16x32_bf16 v[40:43], v[178:181], v[202:205], v[40:43]
	v_mfma_f32_16x16x32_bf16 v[32:35], v[174:177], v[206:209], v[32:35]
	v_mfma_f32_16x16x32_bf16 v[32:35], v[178:181], v[210:213], v[32:35]
	v_mfma_f32_16x16x32_bf16 v[36:39], v[166:169], v[206:209], v[36:39]
	v_mfma_f32_16x16x32_bf16 v[36:39], v[170:173], v[210:213], v[36:39]
	v_mfma_f32_16x16x32_bf16 v[96:99], v[150:153], v[206:209], v[96:99]
	v_mfma_f32_16x16x32_bf16 v[96:99], v[162:165], v[210:213], v[96:99]
	v_mfma_f32_16x16x32_bf16 v[100:103], v[128:131], v[206:209], v[100:103]
	v_mfma_f32_16x16x32_bf16 v[100:103], v[132:135], v[210:213], v[100:103]
	s_setprio 0
	s_waitcnt vmcnt(8)
	s_barrier
	ds_read_b128 v[182:185], v158 offset:16384
	ds_read_b128 v[186:189], v158 offset:17408
	ds_read_b128 v[190:193], v158 offset:18432
	ds_read_b128 v[194:197], v158 offset:19456
	ds_read_b128 v[198:201], v158 offset:20480
	ds_read_b128 v[202:205], v158 offset:21504
	ds_read_b128 v[206:209], v158 offset:22528
	ds_read_b128 v[210:213], v158 offset:23552
	s_add_u32 vcc_lo, s20, 0x404000
	s_addc_u32 vcc_hi, s21, 0
	s_add_i32 m0, s24, 0x10000
	s_nop 0
	global_load_lds_dwordx4 v138, s[20:21]
	s_add_i32 m0, s24, 0x12000
	s_nop 0
	global_load_lds_dwordx4 v142, s[20:21]
	s_add_i32 m0, s24, 0x14000
	s_nop 0
	global_load_lds_dwordx4 v138, vcc
	s_add_i32 m0, s24, 0x16000
	s_nop 0
	global_load_lds_dwordx4 v142, vcc
	s_mov_b32 m0, s24
	s_nop 0
	global_load_lds_dwordx4 v136, s[22:23]
	s_add_i32 m0, s24, 0x2000
	s_nop 0
	global_load_lds_dwordx4 v140, s[22:23]
	s_waitcnt lgkmcnt(0)
	s_setprio 1
	v_mfma_f32_16x16x32_bf16 v[92:95], v[128:131], v[182:185], v[92:95]
	v_mfma_f32_16x16x32_bf16 v[92:95], v[132:135], v[186:189], v[92:95]
	v_mfma_f32_16x16x32_bf16 v[88:91], v[150:153], v[182:185], v[88:91]
	v_mfma_f32_16x16x32_bf16 v[88:91], v[162:165], v[186:189], v[88:91]
	v_mfma_f32_16x16x32_bf16 v[28:31], v[166:169], v[182:185], v[28:31]
	v_mfma_f32_16x16x32_bf16 v[28:31], v[170:173], v[186:189], v[28:31]
	v_mfma_f32_16x16x32_bf16 v[24:27], v[174:177], v[182:185], v[24:27]
	v_mfma_f32_16x16x32_bf16 v[24:27], v[178:181], v[186:189], v[24:27]
	v_mfma_f32_16x16x32_bf16 v[16:19], v[174:177], v[190:193], v[16:19]
	v_mfma_f32_16x16x32_bf16 v[16:19], v[178:181], v[194:197], v[16:19]
	v_mfma_f32_16x16x32_bf16 v[20:23], v[166:169], v[190:193], v[20:23]
	v_mfma_f32_16x16x32_bf16 v[20:23], v[170:173], v[194:197], v[20:23]
	v_mfma_f32_16x16x32_bf16 v[80:83], v[150:153], v[190:193], v[80:83]
	v_mfma_f32_16x16x32_bf16 v[80:83], v[162:165], v[194:197], v[80:83]
	v_mfma_f32_16x16x32_bf16 v[84:87], v[128:131], v[190:193], v[84:87]
	v_mfma_f32_16x16x32_bf16 v[84:87], v[132:135], v[194:197], v[84:87]
	v_mfma_f32_16x16x32_bf16 v[76:79], v[128:131], v[198:201], v[76:79]
	v_mfma_f32_16x16x32_bf16 v[76:79], v[132:135], v[202:205], v[76:79]
	v_mfma_f32_16x16x32_bf16 v[72:75], v[150:153], v[198:201], v[72:75]
	v_mfma_f32_16x16x32_bf16 v[72:75], v[162:165], v[202:205], v[72:75]
	v_mfma_f32_16x16x32_bf16 v[12:15], v[166:169], v[198:201], v[12:15]
	v_mfma_f32_16x16x32_bf16 v[12:15], v[170:173], v[202:205], v[12:15]
	v_mfma_f32_16x16x32_bf16 v[8:11], v[174:177], v[198:201], v[8:11]
	v_mfma_f32_16x16x32_bf16 v[8:11], v[178:181], v[202:205], v[8:11]
	v_mfma_f32_16x16x32_bf16 v[0:3], v[174:177], v[206:209], v[0:3]
	v_mfma_f32_16x16x32_bf16 v[0:3], v[178:181], v[210:213], v[0:3]
	v_mfma_f32_16x16x32_bf16 v[4:7], v[166:169], v[206:209], v[4:7]
	v_mfma_f32_16x16x32_bf16 v[4:7], v[170:173], v[210:213], v[4:7]
	v_mfma_f32_16x16x32_bf16 v[56:59], v[150:153], v[206:209], v[56:59]
	v_mfma_f32_16x16x32_bf16 v[56:59], v[162:165], v[210:213], v[56:59]
	v_mfma_f32_16x16x32_bf16 v[60:63], v[128:131], v[206:209], v[60:63]
	v_mfma_f32_16x16x32_bf16 v[60:63], v[132:135], v[210:213], v[60:63]
	s_setprio 0
	s_waitcnt vmcnt(8)
	s_barrier
; #define PG8_STAGE(bufoff, gbase, voff) do { _Pragma("unroll") for (int _i = 0; _i < 2; ++_i) \
;         __builtin_amdgcn_global_load_lds((const unsigned*)((const char*)(gbase) + (voff)[_i]), (PG8_LAS unsigned*)(lds + (bufoff) + ldsw + _i * 8192), 16, 0, 0); } while (0)
; #define PG8_LDA(dst, b, h) do { _Pragma("unroll") for (int m = 0; m < 4; ++m) _Pragma("unroll") for (int k = 0; k < 2; ++k) dst[m][k] = *(const PG8_LAS bf16x8*)(lds + PG8_SA(b, h) + aoff + m * 2048 + k * 1024); } while (0)
; #define PG8_LDB(dst, b, h) do { _Pragma("unroll") for (int n = 0; n < 2; ++n) _Pragma("unroll") for (int k = 0; k < 2; ++k) dst[n][k] = *(const PG8_LAS bf16x8*)(lds + PG8_SB(b, h) + boff + n * 2048 + k * 1024); } while (0)
; #define PG8_MMA(ai, bj, At, Bt) do { __builtin_amdgcn_s_setprio(1); _Pragma("unroll") for (int m = 0; m < 4; ++m) _Pragma("unroll") for (int n = 0; n < 2; ++n) _Pragma("unroll") for (int k = 0; k < 2; ++k) \
;         acc[ai][bj][m][n] = __builtin_amdgcn_mfma_f32_16x16x32_bf16(Bt[n][k], At[m][k], acc[ai][bj][m][n], 0, 0, 0); __builtin_amdgcn_s_setprio(0); } while (0)
; #define PG8_WAIT_V(n) asm volatile("s_waitcnt vmcnt(" #n ")" ::: "memory")
; #define PG8_WAIT_L(n) asm volatile("s_waitcnt lgkmcnt(" #n ")" ::: "memory")
; #define PG8_BAR __builtin_amdgcn_s_barrier()
; #define PG8_SCHED __builtin_amdgcn_sched_barrier(0)
; template <class Epi, class Sched, bool ALIGN_EPI = false, bool SP2 = false>
; __device__ __forceinline__ void gemm_phase(PG8_LAS unsigned char* lds, const Gemm g, const Sched& S, const Epi& E) {
;     ...
;             PG8_LDB(B0, 1, 0); PG8_LDB(B1, 1, 1); PG8_SCHED; PG8_LDA(At, 1, 0); PG8_STAGE(PG8_SA(0, 1), a2 + hstep, voffA);
;             PG8_WAIT_V(8); PG8_WAIT_L(0); PG8_BAR; PG8_MMA(0, 0, At, B0); PG8_MMA(0, 1, At, B1); PG8_BAR; PG8_SCHED;
;             PG8_LDA(At, 1, 1); PG8_STAGE(PG8_SB(1, 0), b3, voffB); PG8_STAGE(PG8_SB(1, 1), b3 + hstep, voffB); PG8_STAGE(PG8_SA(1, 0), a3, voffA);
;             PG8_WAIT_V(8); PG8_WAIT_L(0); PG8_BAR; PG8_MMA(1, 0, At, B0); PG8_MMA(1, 1, At, B1); PG8_BAR; PG8_SCHED;
	ds_read_b128 v[128:131], v159
	ds_read_b128 v[132:135], v159 offset:1024
	ds_read_b128 v[150:153], v159 offset:2048
	ds_read_b128 v[162:165], v159 offset:3072
	ds_read_b128 v[166:169], v160
	ds_read_b128 v[170:173], v160 offset:1024
	ds_read_b128 v[174:177], v160 offset:2048
	ds_read_b128 v[178:181], v160 offset:3072
	ds_read_b128 v[182:185], v158 offset:32768
	ds_read_b128 v[186:189], v158 offset:33792
	ds_read_b128 v[190:193], v158 offset:34816
	ds_read_b128 v[194:197], v158 offset:35840
	ds_read_b128 v[198:201], v158 offset:36864
	ds_read_b128 v[202:205], v158 offset:37888
	ds_read_b128 v[206:209], v158 offset:38912
	ds_read_b128 v[210:213], v158 offset:39936
	s_add_u32 vcc_lo, s22, 0x404000
	s_addc_u32 vcc_hi, s23, 0
	s_add_i32 m0, s24, 0x4000
	s_nop 0
	global_load_lds_dwordx4 v136, vcc
	s_add_i32 m0, s24, 0x6000
	s_nop 0
	global_load_lds_dwordx4 v140, vcc
	s_waitcnt lgkmcnt(0)
	s_setprio 1
	v_mfma_f32_16x16x32_bf16 v[124:127], v[128:131], v[182:185], v[124:127]
	v_mfma_f32_16x16x32_bf16 v[124:127], v[132:135], v[186:189], v[124:127]
	v_mfma_f32_16x16x32_bf16 v[120:123], v[150:153], v[182:185], v[120:123]
	v_mfma_f32_16x16x32_bf16 v[120:123], v[162:165], v[186:189], v[120:123]
	v_mfma_f32_16x16x32_bf16 v[68:71], v[166:169], v[182:185], v[68:71]
	v_mfma_f32_16x16x32_bf16 v[68:71], v[170:173], v[186:189], v[68:71]
	v_mfma_f32_16x16x32_bf16 v[64:67], v[174:177], v[182:185], v[64:67]
	v_mfma_f32_16x16x32_bf16 v[64:67], v[178:181], v[186:189], v[64:67]
	v_mfma_f32_16x16x32_bf16 v[48:51], v[174:177], v[190:193], v[48:51]
	v_mfma_f32_16x16x32_bf16 v[48:51], v[178:181], v[194:197], v[48:51]
	v_mfma_f32_16x16x32_bf16 v[52:55], v[166:169], v[190:193], v[52:55]
	v_mfma_f32_16x16x32_bf16 v[52:55], v[170:173], v[194:197], v[52:55]
	v_mfma_f32_16x16x32_bf16 v[112:115], v[150:153], v[190:193], v[112:115]
	v_mfma_f32_16x16x32_bf16 v[112:115], v[162:165], v[194:197], v[112:115]
	v_mfma_f32_16x16x32_bf16 v[116:119], v[128:131], v[190:193], v[116:119]
	v_mfma_f32_16x16x32_bf16 v[116:119], v[132:135], v[194:197], v[116:119]
	v_mfma_f32_16x16x32_bf16 v[108:111], v[128:131], v[198:201], v[108:111]
	v_mfma_f32_16x16x32_bf16 v[108:111], v[132:135], v[202:205], v[108:111]
	v_mfma_f32_16x16x32_bf16 v[104:107], v[150:153], v[198:201], v[104:107]
	v_mfma_f32_16x16x32_bf16 v[104:107], v[162:165], v[202:205], v[104:107]
	v_mfma_f32_16x16x32_bf16 v[44:47], v[166:169], v[198:201], v[44:47]
	v_mfma_f32_16x16x32_bf16 v[44:47], v[170:173], v[202:205], v[44:47]
	v_mfma_f32_16x16x32_bf16 v[40:43], v[174:177], v[198:201], v[40:43]
	v_mfma_f32_16x16x32_bf16 v[40:43], v[178:181], v[202:205], v[40:43]
	v_mfma_f32_16x16x32_bf16 v[32:35], v[174:177], v[206:209], v[32:35]
	v_mfma_f32_16x16x32_bf16 v[32:35], v[178:181], v[210:213], v[32:35]
	v_mfma_f32_16x16x32_bf16 v[36:39], v[166:169], v[206:209], v[36:39]
	v_mfma_f32_16x16x32_bf16 v[36:39], v[170:173], v[210:213], v[36:39]
	v_mfma_f32_16x16x32_bf16 v[96:99], v[150:153], v[206:209], v[96:99]
	v_mfma_f32_16x16x32_bf16 v[96:99], v[162:165], v[210:213], v[96:99]
	v_mfma_f32_16x16x32_bf16 v[100:103], v[128:131], v[206:209], v[100:103]
	v_mfma_f32_16x16x32_bf16 v[100:103], v[132:135], v[210:213], v[100:103]
	s_setprio 0
	s_waitcnt vmcnt(8)
	s_barrier
	ds_read_b128 v[182:185], v158 offset:49152
	ds_read_b128 v[186:189], v158 offset:50176
	ds_read_b128 v[190:193], v158 offset:51200
	ds_read_b128 v[194:197], v158 offset:52224
	ds_read_b128 v[198:201], v158 offset:53248
	ds_read_b128 v[202:205], v158 offset:54272
	ds_read_b128 v[206:209], v158 offset:55296
	ds_read_b128 v[210:213], v158 offset:56320
	s_add_u32 s60, s20, 0x80
	s_addc_u32 s61, s21, 0
	s_add_u32 vcc_lo, s60, 0x404000
	s_addc_u32 vcc_hi, s61, 0
	s_add_i32 m0, s24, 0x18000
	s_nop 0
	global_load_lds_dwordx4 v138, s[60:61]
	s_add_i32 m0, s24, 0x1a000
	s_nop 0
	global_load_lds_dwordx4 v142, s[60:61]
	s_add_i32 m0, s24, 0x1c000
	s_nop 0
	global_load_lds_dwordx4 v138, vcc
	s_add_i32 m0, s24, 0x1e000
	s_nop 0
	global_load_lds_dwordx4 v142, vcc
	s_add_u32 s60, s22, 0x80
	s_addc_u32 s61, s23, 0
	s_add_i32 m0, s24, 0x8000
	s_nop 0
	global_load_lds_dwordx4 v136, s[60:61]
	s_add_i32 m0, s24, 0xa000
	s_nop 0
	global_load_lds_dwordx4 v140, s[60:61]
	s_waitcnt lgkmcnt(0)
	s_setprio 1
	v_mfma_f32_16x16x32_bf16 v[92:95], v[128:131], v[182:185], v[92:95]
	v_mfma_f32_16x16x32_bf16 v[92:95], v[132:135], v[186:189], v[92:95]
	v_mfma_f32_16x16x32_bf16 v[88:91], v[150:153], v[182:185], v[88:91]
	v_mfma_f32_16x16x32_bf16 v[88:91], v[162:165], v[186:189], v[88:91]
	v_mfma_f32_16x16x32_bf16 v[28:31], v[166:169], v[182:185], v[28:31]
	v_mfma_f32_16x16x32_bf16 v[28:31], v[170:173], v[186:189], v[28:31]
	v_mfma_f32_16x16x32_bf16 v[24:27], v[174:177], v[182:185], v[24:27]
	v_mfma_f32_16x16x32_bf16 v[24:27], v[178:181], v[186:189], v[24:27]
	v_mfma_f32_16x16x32_bf16 v[16:19], v[174:177], v[190:193], v[16:19]
	v_mfma_f32_16x16x32_bf16 v[16:19], v[178:181], v[194:197], v[16:19]
	v_mfma_f32_16x16x32_bf16 v[20:23], v[166:169], v[190:193], v[20:23]
	v_mfma_f32_16x16x32_bf16 v[20:23], v[170:173], v[194:197], v[20:23]
	v_mfma_f32_16x16x32_bf16 v[80:83], v[150:153], v[190:193], v[80:83]
	v_mfma_f32_16x16x32_bf16 v[80:83], v[162:165], v[194:197], v[80:83]
	v_mfma_f32_16x16x32_bf16 v[84:87], v[128:131], v[190:193], v[84:87]
	v_mfma_f32_16x16x32_bf16 v[84:87], v[132:135], v[194:197], v[84:87]
	v_mfma_f32_16x16x32_bf16 v[76:79], v[128:131], v[198:201], v[76:79]
	v_mfma_f32_16x16x32_bf16 v[76:79], v[132:135], v[202:205], v[76:79]
	v_mfma_f32_16x16x32_bf16 v[72:75], v[150:153], v[198:201], v[72:75]
	v_mfma_f32_16x16x32_bf16 v[72:75], v[162:165], v[202:205], v[72:75]
	v_mfma_f32_16x16x32_bf16 v[12:15], v[166:169], v[198:201], v[12:15]
	v_mfma_f32_16x16x32_bf16 v[12:15], v[170:173], v[202:205], v[12:15]
	v_mfma_f32_16x16x32_bf16 v[8:11], v[174:177], v[198:201], v[8:11]
	v_mfma_f32_16x16x32_bf16 v[8:11], v[178:181], v[202:205], v[8:11]
	v_mfma_f32_16x16x32_bf16 v[0:3], v[174:177], v[206:209], v[0:3]
	v_mfma_f32_16x16x32_bf16 v[0:3], v[178:181], v[210:213], v[0:3]
	v_mfma_f32_16x16x32_bf16 v[4:7], v[166:169], v[206:209], v[4:7]
	v_mfma_f32_16x16x32_bf16 v[4:7], v[170:173], v[210:213], v[4:7]
	v_mfma_f32_16x16x32_bf16 v[56:59], v[150:153], v[206:209], v[56:59]
	v_mfma_f32_16x16x32_bf16 v[56:59], v[162:165], v[210:213], v[56:59]
	v_mfma_f32_16x16x32_bf16 v[60:63], v[128:131], v[206:209], v[60:63]
	v_mfma_f32_16x16x32_bf16 v[60:63], v[132:135], v[210:213], v[60:63]
	s_setprio 0
	s_waitcnt vmcnt(8)
	s_barrier
	s_add_i32 s59, s59, 2
	s_add_u32 s18, s18, 0x100
	s_addc_u32 s19, s19, 0
	s_add_u32 s57, s57, 0x100
	s_addc_u32 s58, s58, 0
	s_cmpk_gt_u32 s59, 0xfd
	s_cbranch_scc0 .LBB0_1321
	s_branch .Lf2_exit
; #define PG8_STAGE(bufoff, gbase, voff) do { _Pragma("unroll") for (int _i = 0; _i < 2; ++_i) \
;         __builtin_amdgcn_global_load_lds((const unsigned*)((const char*)(gbase) + (voff)[_i]), (PG8_LAS unsigned*)(lds + (bufoff) + ldsw + _i * 8192), 16, 0, 0); } while (0)
; #define PG8_LDA(dst, b, h) do { _Pragma("unroll") for (int m = 0; m < 4; ++m) _Pragma("unroll") for (int k = 0; k < 2; ++k) dst[m][k] = *(const PG8_LAS bf16x8*)(lds + PG8_SA(b, h) + aoff + m * 2048 + k * 1024); } while (0)
; #define PG8_LDB(dst, b, h) do { _Pragma("unroll") for (int n = 0; n < 2; ++n) _Pragma("unroll") for (int k = 0; k < 2; ++k) dst[n][k] = *(const PG8_LAS bf16x8*)(lds + PG8_SB(b, h) + boff + n * 2048 + k * 1024); } while (0)
; #define PG8_MMA(ai, bj, At, Bt) do { __builtin_amdgcn_s_setprio(1); _Pragma("unroll") for (int m = 0; m < 4; ++m) _Pragma("unroll") for (int n = 0; n < 2; ++n) _Pragma("unroll") for (int k = 0; k < 2; ++k) \
;         acc[ai][bj][m][n] = __builtin_amdgcn_mfma_f32_16x16x32_bf16(Bt[n][k], At[m][k], acc[ai][bj][m][n], 0, 0, 0); __builtin_amdgcn_s_setprio(0); } while (0)
; #define PG8_WAIT_V(n) asm volatile("s_waitcnt vmcnt(" #n ")" ::: "memory")
; #define PG8_WAIT_L(n) asm volatile("s_waitcnt lgkmcnt(" #n ")" ::: "memory")
; #define PG8_BAR __builtin_amdgcn_s_barrier()
; #define PG8_SCHED __builtin_amdgcn_sched_barrier(0)
; template <class Epi, class Sched, bool ALIGN_EPI = false, bool SP2 = false>
; __device__ __forceinline__ void gemm_phase(PG8_LAS unsigned char* lds, const Gemm g, const Sched& S, const Epi& E) {
;     ...
;             PG8_LDB(B0, 0, 0); PG8_LDB(B1, 0, 1); PG8_SCHED; PG8_LDA(At, 0, 0); PG8_STAGE(PG8_SA(1, 1), a1 + hstep, voffA);
;             PG8_WAIT_V(8); PG8_WAIT_L(0); PG8_BAR; PG8_MMA(0, 0, At, B0); PG8_MMA(0, 1, At, B1); PG8_BAR; PG8_SCHED;
;             PG8_LDA(At, 0, 1); PG8_STAGE(PG8_SB(0, 0), b2, voffB); PG8_STAGE(PG8_SB(0, 1), b2 + hstep, voffB); PG8_STAGE(PG8_SA(0, 0), a2, voffA);
;             PG8_WAIT_V(8); PG8_WAIT_L(0); PG8_BAR; PG8_MMA(1, 0, At, B0); PG8_MMA(1, 1, At, B1); PG8_BAR; PG8_SCHED;
.Lf2_h1:
	ds_read_b128 v[128:131], v156
	ds_read_b128 v[132:135], v156 offset:1024
	ds_read_b128 v[150:153], v156 offset:2048
	ds_read_b128 v[162:165], v156 offset:3072
	ds_read_b128 v[166:169], v157
	ds_read_b128 v[170:173], v157 offset:1024
	ds_read_b128 v[174:177], v157 offset:2048
	ds_read_b128 v[178:181], v157 offset:3072
	s_add_u32 s20, s18, 0xffbfc080
	s_addc_u32 s21, s19, -1
	s_cmpk_eq_i32 s59, 0xfc
	s_cselect_b32 s23, s7, s21
	s_cselect_b32 s22, s6, s20
	s_cselect_b32 s21, s17, s58
	s_cselect_b32 s20, s16, s57
	ds_read_b128 v[182:185], v158
	ds_read_b128 v[186:189], v158 offset:1024
	ds_read_b128 v[190:193], v158 offset:2048
	ds_read_b128 v[194:197], v158 offset:3072
	ds_read_b128 v[198:201], v158 offset:4096
	ds_read_b128 v[202:205], v158 offset:5120
	ds_read_b128 v[206:209], v158 offset:6144
	ds_read_b128 v[210:213], v158 offset:7168
	s_add_i32 m0, s24, 0xc000
	s_nop 0
	global_load_lds_dwordx4 v136, s[18:19]
	s_add_i32 m0, s24, 0xe000
	s_nop 0
	global_load_lds_dwordx4 v140, s[18:19]
	s_sleep 2
	s_waitcnt lgkmcnt(0)
	s_waitcnt vmcnt(8)
	s_barrier
	s_setprio 2
	v_mfma_f32_16x16x32_bf16 v[124:127], v[128:131], v[182:185], v[124:127]
	v_mfma_f32_16x16x32_bf16 v[124:127], v[132:135], v[186:189], v[124:127]
	v_mfma_f32_16x16x32_bf16 v[120:123], v[150:153], v[182:185], v[120:123]
	v_mfma_f32_16x16x32_bf16 v[120:123], v[162:165], v[186:189], v[120:123]
	v_mfma_f32_16x16x32_bf16 v[68:71], v[166:169], v[182:185], v[68:71]
	v_mfma_f32_16x16x32_bf16 v[68:71], v[170:173], v[186:189], v[68:71]
	v_mfma_f32_16x16x32_bf16 v[64:67], v[174:177], v[182:185], v[64:67]
	v_mfma_f32_16x16x32_bf16 v[64:67], v[178:181], v[186:189], v[64:67]
	v_mfma_f32_16x16x32_bf16 v[48:51], v[174:177], v[190:193], v[48:51]
	v_mfma_f32_16x16x32_bf16 v[48:51], v[178:181], v[194:197], v[48:51]
	v_mfma_f32_16x16x32_bf16 v[52:55], v[166:169], v[190:193], v[52:55]
	v_mfma_f32_16x16x32_bf16 v[52:55], v[170:173], v[194:197], v[52:55]
	v_mfma_f32_16x16x32_bf16 v[112:115], v[150:153], v[190:193], v[112:115]
	v_mfma_f32_16x16x32_bf16 v[112:115], v[162:165], v[194:197], v[112:115]
	v_mfma_f32_16x16x32_bf16 v[116:119], v[128:131], v[190:193], v[116:119]
	v_mfma_f32_16x16x32_bf16 v[116:119], v[132:135], v[194:197], v[116:119]
	v_mfma_f32_16x16x32_bf16 v[108:111], v[128:131], v[198:201], v[108:111]
	v_mfma_f32_16x16x32_bf16 v[108:111], v[132:135], v[202:205], v[108:111]
	v_mfma_f32_16x16x32_bf16 v[104:107], v[150:153], v[198:201], v[104:107]
	v_mfma_f32_16x16x32_bf16 v[104:107], v[162:165], v[202:205], v[104:107]
	v_mfma_f32_16x16x32_bf16 v[44:47], v[166:169], v[198:201], v[44:47]
	v_mfma_f32_16x16x32_bf16 v[44:47], v[170:173], v[202:205], v[44:47]
	v_mfma_f32_16x16x32_bf16 v[40:43], v[174:177], v[198:201], v[40:43]
	v_mfma_f32_16x16x32_bf16 v[40:43], v[178:181], v[202:205], v[40:43]
	v_mfma_f32_16x16x32_bf16 v[32:35], v[174:177], v[206:209], v[32:35]
	v_mfma_f32_16x16x32_bf16 v[32:35], v[178:181], v[210:213], v[32:35]
	v_mfma_f32_16x16x32_bf16 v[36:39], v[166:169], v[206:209], v[36:39]
	v_mfma_f32_16x16x32_bf16 v[36:39], v[170:173], v[210:213], v[36:39]
	v_mfma_f32_16x16x32_bf16 v[96:99], v[150:153], v[206:209], v[96:99]
	v_mfma_f32_16x16x32_bf16 v[96:99], v[162:165], v[210:213], v[96:99]
	v_mfma_f32_16x16x32_bf16 v[100:103], v[128:131], v[206:209], v[100:103]
	v_mfma_f32_16x16x32_bf16 v[100:103], v[132:135], v[210:213], v[100:103]
	s_setprio 0
	ds_read_b128 v[182:185], v158 offset:16384
	ds_read_b128 v[186:189], v158 offset:17408
	ds_read_b128 v[190:193], v158 offset:18432
	ds_read_b128 v[194:197], v158 offset:19456
	ds_read_b128 v[198:201], v158 offset:20480
	ds_read_b128 v[202:205], v158 offset:21504
	ds_read_b128 v[206:209], v158 offset:22528
	ds_read_b128 v[210:213], v158 offset:23552
	s_add_u32 vcc_lo, s20, 0x404000
	s_addc_u32 vcc_hi, s21, 0
	s_add_i32 m0, s24, 0x10000
	s_nop 0
	global_load_lds_dwordx4 v138, s[20:21]
	s_add_i32 m0, s24, 0x12000
	s_nop 0
	global_load_lds_dwordx4 v142, s[20:21]
	s_add_i32 m0, s24, 0x14000
	s_nop 0
	global_load_lds_dwordx4 v138, vcc
	s_add_i32 m0, s24, 0x16000
	s_nop 0
	global_load_lds_dwordx4 v142, vcc
	s_mov_b32 m0, s24
	s_nop 0
	global_load_lds_dwordx4 v136, s[22:23]
	s_add_i32 m0, s24, 0x2000
	s_nop 0
	global_load_lds_dwordx4 v140, s[22:23]
	s_sleep 2
	s_waitcnt lgkmcnt(0)
	s_waitcnt vmcnt(8)
	s_barrier
; #define PG8_STAGE(bufoff, gbase, voff) do { _Pragma("unroll") for (int _i = 0; _i < 2; ++_i) \
;         __builtin_amdgcn_global_load_lds((const unsigned*)((const char*)(gbase) + (voff)[_i]), (PG8_LAS unsigned*)(lds + (bufoff) + ldsw + _i * 8192), 16, 0, 0); } while (0)
; #define PG8_LDA(dst, b, h) do { _Pragma("unroll") for (int m = 0; m < 4; ++m) _Pragma("unroll") for (int k = 0; k < 2; ++k) dst[m][k] = *(const PG8_LAS bf16x8*)(lds + PG8_SA(b, h) + aoff + m * 2048 + k * 1024); } while (0)
; #define PG8_LDB(dst, b, h) do { _Pragma("unroll") for (int n = 0; n < 2; ++n) _Pragma("unroll") for (int k = 0; k < 2; ++k) dst[n][k] = *(const PG8_LAS bf16x8*)(lds + PG8_SB(b, h) + boff + n * 2048 + k * 1024); } while (0)
; #define PG8_MMA(ai, bj, At, Bt) do { __builtin_amdgcn_s_setprio(1); _Pragma("unroll") for (int m = 0; m < 4; ++m) _Pragma("unroll") for (int n = 0; n < 2; ++n) _Pragma("unroll") for (int k = 0; k < 2; ++k) \
;         acc[ai][bj][m][n] = __builtin_amdgcn_mfma_f32_16x16x32_bf16(Bt[n][k], At[m][k], acc[ai][bj][m][n], 0, 0, 0); __builtin_amdgcn_s_setprio(0); } while (0)
; #define PG8_WAIT_V(n) asm volatile("s_waitcnt vmcnt(" #n ")" ::: "memory")
; #define PG8_WAIT_L(n) asm volatile("s_waitcnt lgkmcnt(" #n ")" ::: "memory")
; #define PG8_BAR __builtin_amdgcn_s_barrier()
; #define PG8_SCHED __builtin_amdgcn_sched_barrier(0)
; template <class Epi, class Sched, bool ALIGN_EPI = false, bool SP2 = false>
; __device__ __forceinline__ void gemm_phase(PG8_LAS unsigned char* lds, const Gemm g, const Sched& S, const Epi& E) {
;     ...
;             PG8_WAIT_V(8); PG8_WAIT_L(0); PG8_BAR; PG8_MMA(1, 0, At, B0); PG8_MMA(1, 1, At, B1); PG8_BAR; PG8_SCHED;
;             PG8_LDB(B0, 1, 0); PG8_LDB(B1, 1, 1); PG8_SCHED; PG8_LDA(At, 1, 0); PG8_STAGE(PG8_SA(0, 1), a2 + hstep, voffA);
;             PG8_WAIT_V(8); PG8_WAIT_L(0); PG8_BAR; PG8_MMA(0, 0, At, B0); PG8_MMA(0, 1, At, B1); PG8_BAR; PG8_SCHED;
	s_setprio 2
	v_mfma_f32_16x16x32_bf16 v[92:95], v[128:131], v[182:185], v[92:95]
	v_mfma_f32_16x16x32_bf16 v[92:95], v[132:135], v[186:189], v[92:95]
	v_mfma_f32_16x16x32_bf16 v[88:91], v[150:153], v[182:185], v[88:91]
	v_mfma_f32_16x16x32_bf16 v[88:91], v[162:165], v[186:189], v[88:91]
	v_mfma_f32_16x16x32_bf16 v[28:31], v[166:169], v[182:185], v[28:31]
	v_mfma_f32_16x16x32_bf16 v[28:31], v[170:173], v[186:189], v[28:31]
	v_mfma_f32_16x16x32_bf16 v[24:27], v[174:177], v[182:185], v[24:27]
	v_mfma_f32_16x16x32_bf16 v[24:27], v[178:181], v[186:189], v[24:27]
	v_mfma_f32_16x16x32_bf16 v[16:19], v[174:177], v[190:193], v[16:19]
	v_mfma_f32_16x16x32_bf16 v[16:19], v[178:181], v[194:197], v[16:19]
	v_mfma_f32_16x16x32_bf16 v[20:23], v[166:169], v[190:193], v[20:23]
	v_mfma_f32_16x16x32_bf16 v[20:23], v[170:173], v[194:197], v[20:23]
	v_mfma_f32_16x16x32_bf16 v[80:83], v[150:153], v[190:193], v[80:83]
	v_mfma_f32_16x16x32_bf16 v[80:83], v[162:165], v[194:197], v[80:83]
	v_mfma_f32_16x16x32_bf16 v[84:87], v[128:131], v[190:193], v[84:87]
	v_mfma_f32_16x16x32_bf16 v[84:87], v[132:135], v[194:197], v[84:87]
	v_mfma_f32_16x16x32_bf16 v[76:79], v[128:131], v[198:201], v[76:79]
	v_mfma_f32_16x16x32_bf16 v[76:79], v[132:135], v[202:205], v[76:79]
	v_mfma_f32_16x16x32_bf16 v[72:75], v[150:153], v[198:201], v[72:75]
	v_mfma_f32_16x16x32_bf16 v[72:75], v[162:165], v[202:205], v[72:75]
	v_mfma_f32_16x16x32_bf16 v[12:15], v[166:169], v[198:201], v[12:15]
	v_mfma_f32_16x16x32_bf16 v[12:15], v[170:173], v[202:205], v[12:15]
	v_mfma_f32_16x16x32_bf16 v[8:11], v[174:177], v[198:201], v[8:11]
	v_mfma_f32_16x16x32_bf16 v[8:11], v[178:181], v[202:205], v[8:11]
	v_mfma_f32_16x16x32_bf16 v[0:3], v[174:177], v[206:209], v[0:3]
	v_mfma_f32_16x16x32_bf16 v[0:3], v[178:181], v[210:213], v[0:3]
	v_mfma_f32_16x16x32_bf16 v[4:7], v[166:169], v[206:209], v[4:7]
	v_mfma_f32_16x16x32_bf16 v[4:7], v[170:173], v[210:213], v[4:7]
	v_mfma_f32_16x16x32_bf16 v[56:59], v[150:153], v[206:209], v[56:59]
	v_mfma_f32_16x16x32_bf16 v[56:59], v[162:165], v[210:213], v[56:59]
	v_mfma_f32_16x16x32_bf16 v[60:63], v[128:131], v[206:209], v[60:63]
	v_mfma_f32_16x16x32_bf16 v[60:63], v[132:135], v[210:213], v[60:63]
	s_setprio 0
	ds_read_b128 v[128:131], v159
	ds_read_b128 v[132:135], v159 offset:1024
	ds_read_b128 v[150:153], v159 offset:2048
	ds_read_b128 v[162:165], v159 offset:3072
	ds_read_b128 v[166:169], v160
	ds_read_b128 v[170:173], v160 offset:1024
	ds_read_b128 v[174:177], v160 offset:2048
	ds_read_b128 v[178:181], v160 offset:3072
	ds_read_b128 v[182:185], v158 offset:32768
	ds_read_b128 v[186:189], v158 offset:33792
	ds_read_b128 v[190:193], v158 offset:34816
	ds_read_b128 v[194:197], v158 offset:35840
	ds_read_b128 v[198:201], v158 offset:36864
	ds_read_b128 v[202:205], v158 offset:37888
	ds_read_b128 v[206:209], v158 offset:38912
	ds_read_b128 v[210:213], v158 offset:39936
	s_add_u32 vcc_lo, s22, 0x404000
	s_addc_u32 vcc_hi, s23, 0
	s_add_i32 m0, s24, 0x4000
	s_nop 0
	global_load_lds_dwordx4 v136, vcc
	s_add_i32 m0, s24, 0x6000
	s_nop 0
	global_load_lds_dwordx4 v140, vcc
	s_sleep 2
	s_waitcnt lgkmcnt(0)
	s_waitcnt vmcnt(8)
	s_barrier
; #define PG8_STAGE(bufoff, gbase, voff) do { _Pragma("unroll") for (int _i = 0; _i < 2; ++_i) \
;         __builtin_amdgcn_global_load_lds((const unsigned*)((const char*)(gbase) + (voff)[_i]), (PG8_LAS unsigned*)(lds + (bufoff) + ldsw + _i * 8192), 16, 0, 0); } while (0)
; #define PG8_LDA(dst, b, h) do { _Pragma("unroll") for (int m = 0; m < 4; ++m) _Pragma("unroll") for (int k = 0; k < 2; ++k) dst[m][k] = *(const PG8_LAS bf16x8*)(lds + PG8_SA(b, h) + aoff + m * 2048 + k * 1024); } while (0)
; #define PG8_MMA(ai, bj, At, Bt) do { __builtin_amdgcn_s_setprio(1); _Pragma("unroll") for (int m = 0; m < 4; ++m) _Pragma("unroll") for (int n = 0; n < 2; ++n) _Pragma("unroll") for (int k = 0; k < 2; ++k) \
;         acc[ai][bj][m][n] = __builtin_amdgcn_mfma_f32_16x16x32_bf16(Bt[n][k], At[m][k], acc[ai][bj][m][n], 0, 0, 0); __builtin_amdgcn_s_setprio(0); } while (0)
; #define PG8_WAIT_V(n) asm volatile("s_waitcnt vmcnt(" #n ")" ::: "memory")
; #define PG8_WAIT_L(n) asm volatile("s_waitcnt lgkmcnt(" #n ")" ::: "memory")
; #define PG8_BAR __builtin_amdgcn_s_barrier()
; #define PG8_SCHED __builtin_amdgcn_sched_barrier(0)
; template <class Epi, class Sched, bool ALIGN_EPI = false, bool SP2 = false>
; __device__ __forceinline__ void gemm_phase(PG8_LAS unsigned char* lds, const Gemm g, const Sched& S, const Epi& E) {
;     ...
;             PG8_WAIT_V(8); PG8_WAIT_L(0); PG8_BAR; PG8_MMA(0, 0, At, B0); PG8_MMA(0, 1, At, B1); PG8_BAR; PG8_SCHED;
;             PG8_LDA(At, 1, 1); PG8_STAGE(PG8_SB(1, 0), b3, voffB); PG8_STAGE(PG8_SB(1, 1), b3 + hstep, voffB); PG8_STAGE(PG8_SA(1, 0), a3, voffA);
;             PG8_WAIT_V(8); PG8_WAIT_L(0); PG8_BAR; PG8_MMA(1, 0, At, B0); PG8_MMA(1, 1, At, B1); PG8_BAR; PG8_SCHED;
	s_setprio 2
	v_mfma_f32_16x16x32_bf16 v[124:127], v[128:131], v[182:185], v[124:127]
	v_mfma_f32_16x16x32_bf16 v[124:127], v[132:135], v[186:189], v[124:127]
	v_mfma_f32_16x16x32_bf16 v[120:123], v[150:153], v[182:185], v[120:123]
	v_mfma_f32_16x16x32_bf16 v[120:123], v[162:165], v[186:189], v[120:123]
	v_mfma_f32_16x16x32_bf16 v[68:71], v[166:169], v[182:185], v[68:71]
	v_mfma_f32_16x16x32_bf16 v[68:71], v[170:173], v[186:189], v[68:71]
	v_mfma_f32_16x16x32_bf16 v[64:67], v[174:177], v[182:185], v[64:67]
	v_mfma_f32_16x16x32_bf16 v[64:67], v[178:181], v[186:189], v[64:67]
	v_mfma_f32_16x16x32_bf16 v[48:51], v[174:177], v[190:193], v[48:51]
	v_mfma_f32_16x16x32_bf16 v[48:51], v[178:181], v[194:197], v[48:51]
	v_mfma_f32_16x16x32_bf16 v[52:55], v[166:169], v[190:193], v[52:55]
	v_mfma_f32_16x16x32_bf16 v[52:55], v[170:173], v[194:197], v[52:55]
	v_mfma_f32_16x16x32_bf16 v[112:115], v[150:153], v[190:193], v[112:115]
	v_mfma_f32_16x16x32_bf16 v[112:115], v[162:165], v[194:197], v[112:115]
	v_mfma_f32_16x16x32_bf16 v[116:119], v[128:131], v[190:193], v[116:119]
	v_mfma_f32_16x16x32_bf16 v[116:119], v[132:135], v[194:197], v[116:119]
	v_mfma_f32_16x16x32_bf16 v[108:111], v[128:131], v[198:201], v[108:111]
	v_mfma_f32_16x16x32_bf16 v[108:111], v[132:135], v[202:205], v[108:111]
	v_mfma_f32_16x16x32_bf16 v[104:107], v[150:153], v[198:201], v[104:107]
	v_mfma_f32_16x16x32_bf16 v[104:107], v[162:165], v[202:205], v[104:107]
	v_mfma_f32_16x16x32_bf16 v[44:47], v[166:169], v[198:201], v[44:47]
	v_mfma_f32_16x16x32_bf16 v[44:47], v[170:173], v[202:205], v[44:47]
	v_mfma_f32_16x16x32_bf16 v[40:43], v[174:177], v[198:201], v[40:43]
	v_mfma_f32_16x16x32_bf16 v[40:43], v[178:181], v[202:205], v[40:43]
	v_mfma_f32_16x16x32_bf16 v[32:35], v[174:177], v[206:209], v[32:35]
	v_mfma_f32_16x16x32_bf16 v[32:35], v[178:181], v[210:213], v[32:35]
	v_mfma_f32_16x16x32_bf16 v[36:39], v[166:169], v[206:209], v[36:39]
	v_mfma_f32_16x16x32_bf16 v[36:39], v[170:173], v[210:213], v[36:39]
	v_mfma_f32_16x16x32_bf16 v[96:99], v[150:153], v[206:209], v[96:99]
	v_mfma_f32_16x16x32_bf16 v[96:99], v[162:165], v[210:213], v[96:99]
	v_mfma_f32_16x16x32_bf16 v[100:103], v[128:131], v[206:209], v[100:103]
	v_mfma_f32_16x16x32_bf16 v[100:103], v[132:135], v[210:213], v[100:103]
	s_setprio 0
	ds_read_b128 v[182:185], v158 offset:49152
	ds_read_b128 v[186:189], v158 offset:50176
	ds_read_b128 v[190:193], v158 offset:51200
	ds_read_b128 v[194:197], v158 offset:52224
	ds_read_b128 v[198:201], v158 offset:53248
	ds_read_b128 v[202:205], v158 offset:54272
	ds_read_b128 v[206:209], v158 offset:55296
	ds_read_b128 v[210:213], v158 offset:56320
	s_add_u32 s60, s20, 0x80
	s_addc_u32 s61, s21, 0
	s_add_u32 vcc_lo, s60, 0x404000
	s_addc_u32 vcc_hi, s61, 0
	s_add_i32 m0, s24, 0x18000
	s_nop 0
	global_load_lds_dwordx4 v138, s[60:61]
	s_add_i32 m0, s24, 0x1a000
	s_nop 0
	global_load_lds_dwordx4 v142, s[60:61]
	s_add_i32 m0, s24, 0x1c000
	s_nop 0
	global_load_lds_dwordx4 v138, vcc
	s_add_i32 m0, s24, 0x1e000
	s_nop 0
	global_load_lds_dwordx4 v142, vcc
	s_add_u32 s60, s22, 0x80
	s_addc_u32 s61, s23, 0
	s_add_i32 m0, s24, 0x8000
	s_nop 0
	global_load_lds_dwordx4 v136, s[60:61]
	s_add_i32 m0, s24, 0xa000
	s_nop 0
	global_load_lds_dwordx4 v140, s[60:61]
	s_sleep 2
	s_waitcnt lgkmcnt(0)
	s_waitcnt vmcnt(8)
	s_barrier
	s_setprio 2
	v_mfma_f32_16x16x32_bf16 v[92:95], v[128:131], v[182:185], v[92:95]
	v_mfma_f32_16x16x32_bf16 v[92:95], v[132:135], v[186:189], v[92:95]
	v_mfma_f32_16x16x32_bf16 v[88:91], v[150:153], v[182:185], v[88:91]
	v_mfma_f32_16x16x32_bf16 v[88:91], v[162:165], v[186:189], v[88:91]
	v_mfma_f32_16x16x32_bf16 v[28:31], v[166:169], v[182:185], v[28:31]
	v_mfma_f32_16x16x32_bf16 v[28:31], v[170:173], v[186:189], v[28:31]
	v_mfma_f32_16x16x32_bf16 v[24:27], v[174:177], v[182:185], v[24:27]
	v_mfma_f32_16x16x32_bf16 v[24:27], v[178:181], v[186:189], v[24:27]
	v_mfma_f32_16x16x32_bf16 v[16:19], v[174:177], v[190:193], v[16:19]
	v_mfma_f32_16x16x32_bf16 v[16:19], v[178:181], v[194:197], v[16:19]
	v_mfma_f32_16x16x32_bf16 v[20:23], v[166:169], v[190:193], v[20:23]
	v_mfma_f32_16x16x32_bf16 v[20:23], v[170:173], v[194:197], v[20:23]
	v_mfma_f32_16x16x32_bf16 v[80:83], v[150:153], v[190:193], v[80:83]
	v_mfma_f32_16x16x32_bf16 v[80:83], v[162:165], v[194:197], v[80:83]
	v_mfma_f32_16x16x32_bf16 v[84:87], v[128:131], v[190:193], v[84:87]
	v_mfma_f32_16x16x32_bf16 v[84:87], v[132:135], v[194:197], v[84:87]
	v_mfma_f32_16x16x32_bf16 v[76:79], v[128:131], v[198:201], v[76:79]
	v_mfma_f32_16x16x32_bf16 v[76:79], v[132:135], v[202:205], v[76:79]
	v_mfma_f32_16x16x32_bf16 v[72:75], v[150:153], v[198:201], v[72:75]
	v_mfma_f32_16x16x32_bf16 v[72:75], v[162:165], v[202:205], v[72:75]
	v_mfma_f32_16x16x32_bf16 v[12:15], v[166:169], v[198:201], v[12:15]
	v_mfma_f32_16x16x32_bf16 v[12:15], v[170:173], v[202:205], v[12:15]
	v_mfma_f32_16x16x32_bf16 v[8:11], v[174:177], v[198:201], v[8:11]
	v_mfma_f32_16x16x32_bf16 v[8:11], v[178:181], v[202:205], v[8:11]
	v_mfma_f32_16x16x32_bf16 v[0:3], v[174:177], v[206:209], v[0:3]
	v_mfma_f32_16x16x32_bf16 v[0:3], v[178:181], v[210:213], v[0:3]
	v_mfma_f32_16x16x32_bf16 v[4:7], v[166:169], v[206:209], v[4:7]
	v_mfma_f32_16x16x32_bf16 v[4:7], v[170:173], v[210:213], v[4:7]
	v_mfma_f32_16x16x32_bf16 v[56:59], v[150:153], v[206:209], v[56:59]
	v_mfma_f32_16x16x32_bf16 v[56:59], v[162:165], v[210:213], v[56:59]
	v_mfma_f32_16x16x32_bf16 v[60:63], v[128:131], v[206:209], v[60:63]
	v_mfma_f32_16x16x32_bf16 v[60:63], v[132:135], v[210:213], v[60:63]
	s_setprio 0
	s_add_i32 s59, s59, 2
	s_add_u32 s18, s18, 0x100
	s_addc_u32 s19, s19, 0
	s_add_u32 s57, s57, 0x100
	s_addc_u32 s58, s58, 0
	s_cmpk_gt_u32 s59, 0xfd
	s_cbranch_scc0 .Lf2_h1
